# v34 + mid-segment setprio 0/1 flips deleted from the K-loop compute segments (32 MFMAs back-to-back)
# baseline (speedup 1.0000x reference)
.LBB0_246:
	s_add_u32 s3, s34, 0xfff80080
	s_addc_u32 s6, s35, -1
	s_add_i32 s7, 0, 0x10000
	s_cmp_eq_u32 s2, 28
	s_cselect_b32 s43, s15, s6
	s_cselect_b32 s42, s47, s3
	s_cselect_b32 s39, s13, s50
	s_cselect_b32 s38, s48, s49
	s_add_i32 s3, 0, 0x14000
	v_add_u32_e32 v156, s7, v145
	v_add_u32_e32 v172, s3, v145
	ds_read_b128 v[140:143], v156
	ds_read_b128 v[148:151], v156 offset:1024
	ds_read_b128 v[152:155], v156 offset:2048
	ds_read_b128 v[156:159], v156 offset:3072
	ds_read_b128 v[160:163], v172
	ds_read_b128 v[164:167], v172 offset:1024
	ds_read_b128 v[168:171], v172 offset:2048
	ds_read_b128 v[172:175], v172 offset:3072
	v_lshl_add_u64 v[176:177], s[34:35], 0, v[136:137]
	s_add_i32 m0, s18, 0xc000
	ds_read_b128 v[182:185], v147
	ds_read_b128 v[186:189], v147 offset:1024
	ds_read_b128 v[190:193], v147 offset:2048
	ds_read_b128 v[214:217], v147 offset:3072
	ds_read_b128 v[218:221], v147 offset:4096
	ds_read_b128 v[222:225], v147 offset:5120
	ds_read_b128 v[226:229], v147 offset:6144
	ds_read_b128 v[230:233], v147 offset:7168
	global_load_lds_dwordx4 v[176:177], off
	v_lshl_add_u64 v[176:177], s[34:35], 0, v[138:139]
	s_add_i32 m0, s18, 0xe000
	s_nop 0
	global_load_lds_dwordx4 v[176:177], off
	s_setprio 1
	s_waitcnt vmcnt(8)
	s_waitcnt lgkmcnt(0)
	s_barrier
	v_mfma_f32_16x16x32_bf16 v[126:129], v[140:143], v[182:185], v[126:129]
	v_mfma_f32_16x16x32_bf16 v[122:125], v[152:155], v[182:185], v[122:125]
	v_mfma_f32_16x16x32_bf16 v[118:121], v[140:143], v[190:193], v[118:121]
	v_mfma_f32_16x16x32_bf16 v[110:113], v[152:155], v[190:193], v[110:113]
	v_mfma_f32_16x16x32_bf16 v[102:105], v[140:143], v[218:221], v[102:105]
	v_mfma_f32_16x16x32_bf16 v[92:95], v[152:155], v[218:221], v[92:95]
	v_mfma_f32_16x16x32_bf16 v[84:87], v[140:143], v[226:229], v[84:87]
	v_mfma_f32_16x16x32_bf16 v[76:79], v[152:155], v[226:229], v[76:79]
	v_mfma_f32_16x16x32_bf16 v[126:129], v[148:151], v[186:189], v[126:129]
	v_mfma_f32_16x16x32_bf16 v[122:125], v[156:159], v[186:189], v[122:125]
	v_mfma_f32_16x16x32_bf16 v[118:121], v[148:151], v[214:217], v[118:121]
	v_mfma_f32_16x16x32_bf16 v[110:113], v[156:159], v[214:217], v[110:113]
	v_mfma_f32_16x16x32_bf16 v[102:105], v[148:151], v[222:225], v[102:105]
	v_mfma_f32_16x16x32_bf16 v[92:95], v[156:159], v[222:225], v[92:95]
	v_mfma_f32_16x16x32_bf16 v[84:87], v[148:151], v[230:233], v[84:87]
	v_mfma_f32_16x16x32_bf16 v[76:79], v[156:159], v[230:233], v[76:79]
	v_mfma_f32_16x16x32_bf16 v[114:117], v[160:163], v[182:185], v[114:117]
	v_mfma_f32_16x16x32_bf16 v[106:109], v[168:171], v[182:185], v[106:109]
	v_mfma_f32_16x16x32_bf16 v[98:101], v[160:163], v[190:193], v[98:101]
	v_mfma_f32_16x16x32_bf16 v[88:91], v[168:171], v[190:193], v[88:91]
	v_mfma_f32_16x16x32_bf16 v[80:83], v[160:163], v[218:221], v[80:83]
	v_mfma_f32_16x16x32_bf16 v[72:75], v[168:171], v[218:221], v[72:75]
	v_mfma_f32_16x16x32_bf16 v[68:71], v[160:163], v[226:229], v[68:71]
	v_mfma_f32_16x16x32_bf16 v[64:67], v[168:171], v[226:229], v[64:67]
	v_mfma_f32_16x16x32_bf16 v[114:117], v[164:167], v[186:189], v[114:117]
	v_mfma_f32_16x16x32_bf16 v[106:109], v[172:175], v[186:189], v[106:109]
	v_mfma_f32_16x16x32_bf16 v[98:101], v[164:167], v[214:217], v[98:101]
	v_mfma_f32_16x16x32_bf16 v[88:91], v[172:175], v[214:217], v[88:91]
	v_mfma_f32_16x16x32_bf16 v[80:83], v[164:167], v[222:225], v[80:83]
	v_mfma_f32_16x16x32_bf16 v[72:75], v[172:175], v[222:225], v[72:75]
	v_mfma_f32_16x16x32_bf16 v[68:71], v[164:167], v[230:233], v[68:71]
	v_mfma_f32_16x16x32_bf16 v[64:67], v[172:175], v[230:233], v[64:67]
	s_setprio 0
	s_barrier
	s_add_i32 s6, s7, s17
	v_lshl_add_u64 v[176:177], s[38:39], 0, v[96:97]
	s_mov_b32 m0, s6
	ds_read_b128 v[182:185], v147 offset:16384
	ds_read_b128 v[186:189], v147 offset:17408
	ds_read_b128 v[190:193], v147 offset:18432
	ds_read_b128 v[214:217], v147 offset:19456
	ds_read_b128 v[218:221], v147 offset:20480
	ds_read_b128 v[222:225], v147 offset:21504
	ds_read_b128 v[226:229], v147 offset:22528
	ds_read_b128 v[230:233], v147 offset:23552
	global_load_lds_dwordx4 v[176:177], off
	s_add_i32 m0, s6, 0x2000
	s_add_u32 s6, s38, 0x80000
	v_lshl_add_u64 v[178:179], s[38:39], 0, v[130:131]
	s_addc_u32 s7, s39, 0
	s_add_i32 s3, s3, s17
	global_load_lds_dwordx4 v[178:179], off
	v_lshl_add_u64 v[180:181], s[6:7], 0, v[96:97]
	s_mov_b32 m0, s3
	v_lshl_add_u64 v[194:195], s[42:43], 0, v[132:133]
	global_load_lds_dwordx4 v[180:181], off
	v_lshl_add_u64 v[180:181], s[6:7], 0, v[130:131]
	s_add_i32 m0, s3, 0x2000
	s_nop 0
	global_load_lds_dwordx4 v[180:181], off
	v_lshl_add_u64 v[180:181], s[42:43], 0, v[134:135]
	s_mov_b32 m0, s18
	s_nop 0
	global_load_lds_dwordx4 v[180:181], off
	s_mov_b32 m0, s19
	s_nop 0
	global_load_lds_dwordx4 v[194:195], off
	s_setprio 1
	s_waitcnt vmcnt(8)
	s_waitcnt lgkmcnt(0)
	s_barrier
	v_mfma_f32_16x16x32_bf16 v[60:63], v[140:143], v[182:185], v[60:63]
	v_mfma_f32_16x16x32_bf16 v[56:59], v[152:155], v[182:185], v[56:59]
	v_mfma_f32_16x16x32_bf16 v[52:55], v[140:143], v[190:193], v[52:55]
	v_mfma_f32_16x16x32_bf16 v[44:47], v[152:155], v[190:193], v[44:47]
	v_mfma_f32_16x16x32_bf16 v[36:39], v[140:143], v[218:221], v[36:39]
	v_mfma_f32_16x16x32_bf16 v[28:31], v[152:155], v[218:221], v[28:31]
	v_mfma_f32_16x16x32_bf16 v[20:23], v[140:143], v[226:229], v[20:23]
	v_mfma_f32_16x16x32_bf16 v[12:15], v[152:155], v[226:229], v[12:15]
	v_mfma_f32_16x16x32_bf16 v[60:63], v[148:151], v[186:189], v[60:63]
	v_mfma_f32_16x16x32_bf16 v[56:59], v[156:159], v[186:189], v[56:59]
	v_mfma_f32_16x16x32_bf16 v[52:55], v[148:151], v[214:217], v[52:55]
	v_mfma_f32_16x16x32_bf16 v[44:47], v[156:159], v[214:217], v[44:47]
	v_mfma_f32_16x16x32_bf16 v[36:39], v[148:151], v[222:225], v[36:39]
	v_mfma_f32_16x16x32_bf16 v[28:31], v[156:159], v[222:225], v[28:31]
	v_mfma_f32_16x16x32_bf16 v[20:23], v[148:151], v[230:233], v[20:23]
	v_mfma_f32_16x16x32_bf16 v[12:15], v[156:159], v[230:233], v[12:15]
	v_mfma_f32_16x16x32_bf16 v[48:51], v[160:163], v[182:185], v[48:51]
	v_mfma_f32_16x16x32_bf16 v[40:43], v[168:171], v[182:185], v[40:43]
	v_mfma_f32_16x16x32_bf16 v[32:35], v[160:163], v[190:193], v[32:35]
	v_mfma_f32_16x16x32_bf16 v[24:27], v[168:171], v[190:193], v[24:27]
	v_mfma_f32_16x16x32_bf16 v[16:19], v[160:163], v[218:221], v[16:19]
	v_mfma_f32_16x16x32_bf16 v[8:11], v[168:171], v[218:221], v[8:11]
	v_mfma_f32_16x16x32_bf16 v[4:7], v[160:163], v[226:229], v[4:7]
	v_mfma_f32_16x16x32_bf16 v[0:3], v[168:171], v[226:229], v[0:3]
	v_mfma_f32_16x16x32_bf16 v[48:51], v[164:167], v[186:189], v[48:51]
	v_mfma_f32_16x16x32_bf16 v[40:43], v[172:175], v[186:189], v[40:43]
	v_mfma_f32_16x16x32_bf16 v[32:35], v[164:167], v[214:217], v[32:35]
	v_mfma_f32_16x16x32_bf16 v[24:27], v[172:175], v[214:217], v[24:27]
	v_mfma_f32_16x16x32_bf16 v[16:19], v[164:167], v[222:225], v[16:19]
	v_mfma_f32_16x16x32_bf16 v[8:11], v[172:175], v[222:225], v[8:11]
	v_mfma_f32_16x16x32_bf16 v[4:7], v[164:167], v[230:233], v[4:7]
	v_mfma_f32_16x16x32_bf16 v[0:3], v[172:175], v[230:233], v[0:3]
	s_setprio 0
	s_barrier
	s_add_i32 s3, 0, 0x18000
	s_add_i32 s51, 0, 0x1c000
	v_add_u32_e32 v156, s3, v145
	v_add_u32_e32 v172, s51, v145
	ds_read_b128 v[140:143], v156
	ds_read_b128 v[148:151], v156 offset:1024
	ds_read_b128 v[152:155], v156 offset:2048
	ds_read_b128 v[156:159], v156 offset:3072
	ds_read_b128 v[160:163], v172
	ds_read_b128 v[164:167], v172 offset:1024
	ds_read_b128 v[168:171], v172 offset:2048
	ds_read_b128 v[172:175], v172 offset:3072
	s_add_u32 s6, s42, 0x80000
	s_addc_u32 s7, s43, 0
	s_mov_b32 m0, s20
	v_lshl_add_u64 v[202:203], s[6:7], 0, v[134:135]
	ds_read_b128 v[182:185], v147 offset:32768
	ds_read_b128 v[186:189], v147 offset:33792
	ds_read_b128 v[190:193], v147 offset:34816
	ds_read_b128 v[214:217], v147 offset:35840
	ds_read_b128 v[218:221], v147 offset:36864
	ds_read_b128 v[222:225], v147 offset:37888
	ds_read_b128 v[226:229], v147 offset:38912
	ds_read_b128 v[230:233], v147 offset:39936
	global_load_lds_dwordx4 v[202:203], off
	v_lshl_add_u64 v[202:203], s[6:7], 0, v[132:133]
	s_mov_b32 m0, s36
	s_nop 0
	global_load_lds_dwordx4 v[202:203], off
	s_setprio 1
	s_waitcnt vmcnt(8)
	s_waitcnt lgkmcnt(0)
	s_barrier
	v_mfma_f32_16x16x32_bf16 v[126:129], v[140:143], v[182:185], v[126:129]
	v_mfma_f32_16x16x32_bf16 v[122:125], v[152:155], v[182:185], v[122:125]
	v_mfma_f32_16x16x32_bf16 v[118:121], v[140:143], v[190:193], v[118:121]
	v_mfma_f32_16x16x32_bf16 v[110:113], v[152:155], v[190:193], v[110:113]
	v_mfma_f32_16x16x32_bf16 v[102:105], v[140:143], v[218:221], v[102:105]
	v_mfma_f32_16x16x32_bf16 v[92:95], v[152:155], v[218:221], v[92:95]
	v_mfma_f32_16x16x32_bf16 v[84:87], v[140:143], v[226:229], v[84:87]
	v_mfma_f32_16x16x32_bf16 v[76:79], v[152:155], v[226:229], v[76:79]
	v_mfma_f32_16x16x32_bf16 v[126:129], v[148:151], v[186:189], v[126:129]
	v_mfma_f32_16x16x32_bf16 v[122:125], v[156:159], v[186:189], v[122:125]
	v_mfma_f32_16x16x32_bf16 v[118:121], v[148:151], v[214:217], v[118:121]
	v_mfma_f32_16x16x32_bf16 v[110:113], v[156:159], v[214:217], v[110:113]
	v_mfma_f32_16x16x32_bf16 v[102:105], v[148:151], v[222:225], v[102:105]
	v_mfma_f32_16x16x32_bf16 v[92:95], v[156:159], v[222:225], v[92:95]
	v_mfma_f32_16x16x32_bf16 v[84:87], v[148:151], v[230:233], v[84:87]
	v_mfma_f32_16x16x32_bf16 v[76:79], v[156:159], v[230:233], v[76:79]
	v_mfma_f32_16x16x32_bf16 v[114:117], v[160:163], v[182:185], v[114:117]
	v_mfma_f32_16x16x32_bf16 v[106:109], v[168:171], v[182:185], v[106:109]
	v_mfma_f32_16x16x32_bf16 v[98:101], v[160:163], v[190:193], v[98:101]
	v_mfma_f32_16x16x32_bf16 v[88:91], v[168:171], v[190:193], v[88:91]
	v_mfma_f32_16x16x32_bf16 v[80:83], v[160:163], v[218:221], v[80:83]
	v_mfma_f32_16x16x32_bf16 v[72:75], v[168:171], v[218:221], v[72:75]
	v_mfma_f32_16x16x32_bf16 v[68:71], v[160:163], v[226:229], v[68:71]
	v_mfma_f32_16x16x32_bf16 v[64:67], v[168:171], v[226:229], v[64:67]
	v_mfma_f32_16x16x32_bf16 v[114:117], v[164:167], v[186:189], v[114:117]
	v_mfma_f32_16x16x32_bf16 v[106:109], v[172:175], v[186:189], v[106:109]
	v_mfma_f32_16x16x32_bf16 v[98:101], v[164:167], v[214:217], v[98:101]
	v_mfma_f32_16x16x32_bf16 v[88:91], v[172:175], v[214:217], v[88:91]
	v_mfma_f32_16x16x32_bf16 v[80:83], v[164:167], v[222:225], v[80:83]
	v_mfma_f32_16x16x32_bf16 v[72:75], v[172:175], v[222:225], v[72:75]
	v_mfma_f32_16x16x32_bf16 v[68:71], v[164:167], v[230:233], v[68:71]
	v_mfma_f32_16x16x32_bf16 v[64:67], v[172:175], v[230:233], v[64:67]
	s_setprio 0
	s_barrier
	s_add_i32 s3, s3, s17
	v_lshl_add_u64 v[176:177], v[176:177], 0, s[30:31]
	s_mov_b32 m0, s3
	ds_read_b128 v[182:185], v147 offset:49152
	ds_read_b128 v[186:189], v147 offset:50176
	ds_read_b128 v[190:193], v147 offset:51200
	ds_read_b128 v[214:217], v147 offset:52224
	ds_read_b128 v[218:221], v147 offset:53248
	ds_read_b128 v[222:225], v147 offset:54272
	ds_read_b128 v[226:229], v147 offset:55296
	ds_read_b128 v[230:233], v147 offset:56320
	global_load_lds_dwordx4 v[176:177], off
	s_add_i32 m0, s3, 0x2000
	s_add_u32 s6, s38, 0x80080
	v_lshl_add_u64 v[176:177], v[178:179], 0, s[30:31]
	s_addc_u32 s7, s39, 0
	s_add_i32 s3, s51, s17
	global_load_lds_dwordx4 v[176:177], off
	v_lshl_add_u64 v[176:177], s[6:7], 0, v[96:97]
	s_mov_b32 m0, s3
	s_nop 0
	global_load_lds_dwordx4 v[176:177], off
	v_lshl_add_u64 v[176:177], s[6:7], 0, v[130:131]
	s_add_i32 m0, s3, 0x2000
	s_nop 0
	global_load_lds_dwordx4 v[176:177], off
	v_lshl_add_u64 v[176:177], v[180:181], 0, s[30:31]
	s_mov_b32 m0, s37
	s_nop 0
	global_load_lds_dwordx4 v[176:177], off
	v_lshl_add_u64 v[176:177], v[194:195], 0, s[30:31]
	s_mov_b32 m0, s40
	s_nop 0
	global_load_lds_dwordx4 v[176:177], off
	s_setprio 1
	s_waitcnt vmcnt(8)
	s_waitcnt lgkmcnt(0)
	s_barrier
	v_mfma_f32_16x16x32_bf16 v[60:63], v[140:143], v[182:185], v[60:63]
	v_mfma_f32_16x16x32_bf16 v[56:59], v[152:155], v[182:185], v[56:59]
	v_mfma_f32_16x16x32_bf16 v[52:55], v[140:143], v[190:193], v[52:55]
	v_mfma_f32_16x16x32_bf16 v[44:47], v[152:155], v[190:193], v[44:47]
	v_mfma_f32_16x16x32_bf16 v[36:39], v[140:143], v[218:221], v[36:39]
	v_mfma_f32_16x16x32_bf16 v[28:31], v[152:155], v[218:221], v[28:31]
	v_mfma_f32_16x16x32_bf16 v[20:23], v[140:143], v[226:229], v[20:23]
	v_mfma_f32_16x16x32_bf16 v[12:15], v[152:155], v[226:229], v[12:15]
	v_mfma_f32_16x16x32_bf16 v[60:63], v[148:151], v[186:189], v[60:63]
	v_mfma_f32_16x16x32_bf16 v[56:59], v[156:159], v[186:189], v[56:59]
	v_mfma_f32_16x16x32_bf16 v[52:55], v[148:151], v[214:217], v[52:55]
	v_mfma_f32_16x16x32_bf16 v[44:47], v[156:159], v[214:217], v[44:47]
	v_mfma_f32_16x16x32_bf16 v[36:39], v[148:151], v[222:225], v[36:39]
	v_mfma_f32_16x16x32_bf16 v[28:31], v[156:159], v[222:225], v[28:31]
	v_mfma_f32_16x16x32_bf16 v[20:23], v[148:151], v[230:233], v[20:23]
	v_mfma_f32_16x16x32_bf16 v[12:15], v[156:159], v[230:233], v[12:15]
	v_mfma_f32_16x16x32_bf16 v[48:51], v[160:163], v[182:185], v[48:51]
	v_mfma_f32_16x16x32_bf16 v[40:43], v[168:171], v[182:185], v[40:43]
	v_mfma_f32_16x16x32_bf16 v[32:35], v[160:163], v[190:193], v[32:35]
	v_mfma_f32_16x16x32_bf16 v[24:27], v[168:171], v[190:193], v[24:27]
	v_mfma_f32_16x16x32_bf16 v[16:19], v[160:163], v[218:221], v[16:19]
	v_mfma_f32_16x16x32_bf16 v[8:11], v[168:171], v[218:221], v[8:11]
	v_mfma_f32_16x16x32_bf16 v[4:7], v[160:163], v[226:229], v[4:7]
	v_mfma_f32_16x16x32_bf16 v[0:3], v[168:171], v[226:229], v[0:3]
	v_mfma_f32_16x16x32_bf16 v[48:51], v[164:167], v[186:189], v[48:51]
	v_mfma_f32_16x16x32_bf16 v[40:43], v[172:175], v[186:189], v[40:43]
	v_mfma_f32_16x16x32_bf16 v[32:35], v[164:167], v[214:217], v[32:35]
	v_mfma_f32_16x16x32_bf16 v[24:27], v[172:175], v[214:217], v[24:27]
	v_mfma_f32_16x16x32_bf16 v[16:19], v[164:167], v[222:225], v[16:19]
	v_mfma_f32_16x16x32_bf16 v[8:11], v[172:175], v[222:225], v[8:11]
	v_mfma_f32_16x16x32_bf16 v[4:7], v[164:167], v[230:233], v[4:7]
	v_mfma_f32_16x16x32_bf16 v[0:3], v[172:175], v[230:233], v[0:3]
	s_setprio 0
	s_barrier
	s_add_i32 s2, s2, 2
	s_add_u32 s34, s34, 0x100
	s_addc_u32 s35, s35, 0
	s_add_u32 s49, s49, 0x100
	s_addc_u32 s50, s50, 0
	s_cmp_gt_u32 s2, 29
	s_cbranch_scc0 .LBB0_246
	s_nop 0
	s_nop 0
	s_nop 0
	s_nop 0
	s_nop 0
	s_nop 0
	s_nop 0
	s_nop 0
	s_nop 0
	s_nop 0
	s_nop 0
	s_nop 0
	s_and_b64 vcc, exec, s[10:11]
	s_cbranch_vccz .LBB0_249
	s_barrier

.LBB0_421:
	s_add_u32 s3, s22, 0xfffe0080
	s_addc_u32 s6, s23, -1
	s_add_i32 s7, 0, 0x10000
	s_cmp_eq_u32 s2, 4
	s_cselect_b32 s35, s4, s6
	s_cselect_b32 s34, s5, s3
	v_add_u32_e32 v96, s7, v176
	s_cselect_b32 s25, s9, s17
	s_cselect_b32 s24, s13, s15
	s_add_i32 s3, 0, 0x14000
	ds_read_b128 v[56:59], v96
	ds_read_b128 v[60:63], v96 offset:1024
	ds_read_b128 v[138:141], v96 offset:2048
	ds_read_b128 v[142:145], v96 offset:3072
	v_add_u32_e32 v96, s3, v176
	ds_read_b128 v[146:149], v96
	ds_read_b128 v[150:153], v96 offset:1024
	ds_read_b128 v[154:157], v96 offset:2048
	ds_read_b128 v[170:173], v96 offset:3072
	v_lshl_add_u64 v[174:175], s[22:23], 0, v[166:167]
	s_add_i32 m0, s75, 0xc000
	ds_read_b128 v[182:185], v177
	ds_read_b128 v[186:189], v177 offset:1024
	ds_read_b128 v[190:193], v177 offset:2048
	ds_read_b128 v[214:217], v177 offset:3072
	ds_read_b128 v[218:221], v177 offset:4096
	ds_read_b128 v[222:225], v177 offset:5120
	ds_read_b128 v[226:229], v177 offset:6144
	ds_read_b128 v[230:233], v177 offset:7168
	global_load_lds_dwordx4 v[174:175], off
	v_lshl_add_u64 v[174:175], s[22:23], 0, v[168:169]
	s_add_i32 m0, s75, 0xe000
	s_nop 0
	global_load_lds_dwordx4 v[174:175], off
	s_setprio 1
	s_waitcnt vmcnt(8)
	s_waitcnt lgkmcnt(0)
	s_barrier
	v_mfma_f32_16x16x32_bf16 v[134:137], v[56:59], v[182:185], v[134:137]
	v_mfma_f32_16x16x32_bf16 v[130:133], v[138:141], v[182:185], v[130:133]
	v_mfma_f32_16x16x32_bf16 v[118:121], v[56:59], v[190:193], v[118:121]
	v_mfma_f32_16x16x32_bf16 v[114:117], v[138:141], v[190:193], v[114:117]
	v_mfma_f32_16x16x32_bf16 v[102:105], v[56:59], v[218:221], v[102:105]
	v_mfma_f32_16x16x32_bf16 v[98:101], v[138:141], v[218:221], v[98:101]
	v_mfma_f32_16x16x32_bf16 v[84:87], v[56:59], v[226:229], v[84:87]
	v_mfma_f32_16x16x32_bf16 v[80:83], v[138:141], v[226:229], v[80:83]
	v_mfma_f32_16x16x32_bf16 v[134:137], v[60:63], v[186:189], v[134:137]
	v_mfma_f32_16x16x32_bf16 v[130:133], v[142:145], v[186:189], v[130:133]
	v_mfma_f32_16x16x32_bf16 v[118:121], v[60:63], v[214:217], v[118:121]
	v_mfma_f32_16x16x32_bf16 v[114:117], v[142:145], v[214:217], v[114:117]
	v_mfma_f32_16x16x32_bf16 v[102:105], v[60:63], v[222:225], v[102:105]
	v_mfma_f32_16x16x32_bf16 v[98:101], v[142:145], v[222:225], v[98:101]
	v_mfma_f32_16x16x32_bf16 v[84:87], v[60:63], v[230:233], v[84:87]
	v_mfma_f32_16x16x32_bf16 v[80:83], v[142:145], v[230:233], v[80:83]
	v_mfma_f32_16x16x32_bf16 v[126:129], v[146:149], v[182:185], v[126:129]
	v_mfma_f32_16x16x32_bf16 v[122:125], v[154:157], v[182:185], v[122:125]
	v_mfma_f32_16x16x32_bf16 v[110:113], v[146:149], v[190:193], v[110:113]
	v_mfma_f32_16x16x32_bf16 v[106:109], v[154:157], v[190:193], v[106:109]
	v_mfma_f32_16x16x32_bf16 v[92:95], v[146:149], v[218:221], v[92:95]
	v_mfma_f32_16x16x32_bf16 v[88:91], v[154:157], v[218:221], v[88:91]
	v_mfma_f32_16x16x32_bf16 v[76:79], v[146:149], v[226:229], v[76:79]
	v_mfma_f32_16x16x32_bf16 v[72:75], v[154:157], v[226:229], v[72:75]
	v_mfma_f32_16x16x32_bf16 v[126:129], v[150:153], v[186:189], v[126:129]
	v_mfma_f32_16x16x32_bf16 v[122:125], v[170:173], v[186:189], v[122:125]
	v_mfma_f32_16x16x32_bf16 v[110:113], v[150:153], v[214:217], v[110:113]
	v_mfma_f32_16x16x32_bf16 v[106:109], v[170:173], v[214:217], v[106:109]
	v_mfma_f32_16x16x32_bf16 v[92:95], v[150:153], v[222:225], v[92:95]
	v_mfma_f32_16x16x32_bf16 v[88:91], v[170:173], v[222:225], v[88:91]
	v_mfma_f32_16x16x32_bf16 v[76:79], v[150:153], v[230:233], v[76:79]
	v_mfma_f32_16x16x32_bf16 v[72:75], v[170:173], v[230:233], v[72:75]
	s_setprio 0
	s_barrier
	s_add_i32 s6, s7, s74
	v_lshl_add_u64 v[174:175], s[24:25], 0, v[160:161]
	s_mov_b32 m0, s6
	ds_read_b128 v[182:185], v177 offset:16384
	ds_read_b128 v[186:189], v177 offset:17408
	ds_read_b128 v[190:193], v177 offset:18432
	ds_read_b128 v[214:217], v177 offset:19456
	ds_read_b128 v[218:221], v177 offset:20480
	ds_read_b128 v[222:225], v177 offset:21504
	ds_read_b128 v[226:229], v177 offset:22528
	ds_read_b128 v[230:233], v177 offset:23552
	global_load_lds_dwordx4 v[174:175], off
	s_add_i32 m0, s6, 0x2000
	s_add_u32 s6, s24, 0x20000
	v_lshl_add_u64 v[178:179], s[24:25], 0, v[164:165]
	s_addc_u32 s7, s25, 0
	s_add_i32 s3, s3, s74
	global_load_lds_dwordx4 v[178:179], off
	v_lshl_add_u64 v[180:181], s[6:7], 0, v[160:161]
	s_mov_b32 m0, s3
	v_lshl_add_u64 v[194:195], s[34:35], 0, v[162:163]
	global_load_lds_dwordx4 v[180:181], off
	v_lshl_add_u64 v[180:181], s[6:7], 0, v[164:165]
	s_add_i32 m0, s3, 0x2000
	s_nop 0
	global_load_lds_dwordx4 v[180:181], off
	v_lshl_add_u64 v[180:181], s[34:35], 0, v[158:159]
	s_mov_b32 m0, s75
	s_nop 0
	global_load_lds_dwordx4 v[180:181], off
	s_mov_b32 m0, s82
	s_nop 0
	global_load_lds_dwordx4 v[194:195], off
	s_setprio 1
	s_waitcnt vmcnt(8)
	s_waitcnt lgkmcnt(0)
	s_barrier
	v_mfma_f32_16x16x32_bf16 v[68:71], v[56:59], v[182:185], v[68:71]
	v_mfma_f32_16x16x32_bf16 v[64:67], v[138:141], v[182:185], v[64:67]
	v_mfma_f32_16x16x32_bf16 v[44:47], v[56:59], v[190:193], v[44:47]
	v_mfma_f32_16x16x32_bf16 v[40:43], v[138:141], v[190:193], v[40:43]
	v_mfma_f32_16x16x32_bf16 v[28:31], v[56:59], v[218:221], v[28:31]
	v_mfma_f32_16x16x32_bf16 v[24:27], v[138:141], v[218:221], v[24:27]
	v_mfma_f32_16x16x32_bf16 v[12:15], v[56:59], v[226:229], v[12:15]
	v_mfma_f32_16x16x32_bf16 v[8:11], v[138:141], v[226:229], v[8:11]
	v_mfma_f32_16x16x32_bf16 v[68:71], v[60:63], v[186:189], v[68:71]
	v_mfma_f32_16x16x32_bf16 v[64:67], v[142:145], v[186:189], v[64:67]
	v_mfma_f32_16x16x32_bf16 v[44:47], v[60:63], v[214:217], v[44:47]
	v_mfma_f32_16x16x32_bf16 v[40:43], v[142:145], v[214:217], v[40:43]
	v_mfma_f32_16x16x32_bf16 v[28:31], v[60:63], v[222:225], v[28:31]
	v_mfma_f32_16x16x32_bf16 v[24:27], v[142:145], v[222:225], v[24:27]
	v_mfma_f32_16x16x32_bf16 v[12:15], v[60:63], v[230:233], v[12:15]
	v_mfma_f32_16x16x32_bf16 v[8:11], v[142:145], v[230:233], v[8:11]
	v_mfma_f32_16x16x32_bf16 v[52:55], v[146:149], v[182:185], v[52:55]
	v_mfma_f32_16x16x32_bf16 v[48:51], v[154:157], v[182:185], v[48:51]
	v_mfma_f32_16x16x32_bf16 v[36:39], v[146:149], v[190:193], v[36:39]
	v_mfma_f32_16x16x32_bf16 v[32:35], v[154:157], v[190:193], v[32:35]
	v_mfma_f32_16x16x32_bf16 v[20:23], v[146:149], v[218:221], v[20:23]
	v_mfma_f32_16x16x32_bf16 v[16:19], v[154:157], v[218:221], v[16:19]
	v_mfma_f32_16x16x32_bf16 v[4:7], v[146:149], v[226:229], v[4:7]
	v_mfma_f32_16x16x32_bf16 v[0:3], v[154:157], v[226:229], v[0:3]
	v_mfma_f32_16x16x32_bf16 v[52:55], v[150:153], v[186:189], v[52:55]
	v_mfma_f32_16x16x32_bf16 v[48:51], v[170:173], v[186:189], v[48:51]
	v_mfma_f32_16x16x32_bf16 v[36:39], v[150:153], v[214:217], v[36:39]
	v_mfma_f32_16x16x32_bf16 v[32:35], v[170:173], v[214:217], v[32:35]
	v_mfma_f32_16x16x32_bf16 v[20:23], v[150:153], v[222:225], v[20:23]
	v_mfma_f32_16x16x32_bf16 v[16:19], v[170:173], v[222:225], v[16:19]
	v_mfma_f32_16x16x32_bf16 v[4:7], v[150:153], v[230:233], v[4:7]
	v_mfma_f32_16x16x32_bf16 v[0:3], v[170:173], v[230:233], v[0:3]
	s_setprio 0
	s_barrier
	s_add_i32 s3, 0, 0x18000
	v_add_u32_e32 v96, s3, v176
	s_add_i32 s18, 0, 0x1c000
	ds_read_b128 v[56:59], v96
	ds_read_b128 v[60:63], v96 offset:1024
	ds_read_b128 v[138:141], v96 offset:2048
	ds_read_b128 v[142:145], v96 offset:3072
	v_add_u32_e32 v96, s18, v176
	ds_read_b128 v[146:149], v96
	ds_read_b128 v[150:153], v96 offset:1024
	ds_read_b128 v[154:157], v96 offset:2048
	ds_read_b128 v[170:173], v96 offset:3072
	s_add_u32 s6, s34, 0x20000
	s_addc_u32 s7, s35, 0
	s_mov_b32 m0, s83
	v_lshl_add_u64 v[202:203], s[6:7], 0, v[158:159]
	ds_read_b128 v[182:185], v177 offset:32768
	ds_read_b128 v[186:189], v177 offset:33792
	ds_read_b128 v[190:193], v177 offset:34816
	ds_read_b128 v[214:217], v177 offset:35840
	ds_read_b128 v[218:221], v177 offset:36864
	ds_read_b128 v[222:225], v177 offset:37888
	ds_read_b128 v[226:229], v177 offset:38912
	ds_read_b128 v[230:233], v177 offset:39936
	global_load_lds_dwordx4 v[202:203], off
	v_lshl_add_u64 v[202:203], s[6:7], 0, v[162:163]
	s_mov_b32 m0, s88
	s_nop 0
	global_load_lds_dwordx4 v[202:203], off
	s_setprio 1
	s_waitcnt vmcnt(8)
	s_waitcnt lgkmcnt(0)
	s_barrier
	v_mfma_f32_16x16x32_bf16 v[134:137], v[56:59], v[182:185], v[134:137]
	v_mfma_f32_16x16x32_bf16 v[130:133], v[138:141], v[182:185], v[130:133]
	v_mfma_f32_16x16x32_bf16 v[118:121], v[56:59], v[190:193], v[118:121]
	v_mfma_f32_16x16x32_bf16 v[114:117], v[138:141], v[190:193], v[114:117]
	v_mfma_f32_16x16x32_bf16 v[102:105], v[56:59], v[218:221], v[102:105]
	v_mfma_f32_16x16x32_bf16 v[98:101], v[138:141], v[218:221], v[98:101]
	v_mfma_f32_16x16x32_bf16 v[84:87], v[56:59], v[226:229], v[84:87]
	v_mfma_f32_16x16x32_bf16 v[80:83], v[138:141], v[226:229], v[80:83]
	v_mfma_f32_16x16x32_bf16 v[134:137], v[60:63], v[186:189], v[134:137]
	v_mfma_f32_16x16x32_bf16 v[130:133], v[142:145], v[186:189], v[130:133]
	v_mfma_f32_16x16x32_bf16 v[118:121], v[60:63], v[214:217], v[118:121]
	v_mfma_f32_16x16x32_bf16 v[114:117], v[142:145], v[214:217], v[114:117]
	v_mfma_f32_16x16x32_bf16 v[102:105], v[60:63], v[222:225], v[102:105]
	v_mfma_f32_16x16x32_bf16 v[98:101], v[142:145], v[222:225], v[98:101]
	v_mfma_f32_16x16x32_bf16 v[84:87], v[60:63], v[230:233], v[84:87]
	v_mfma_f32_16x16x32_bf16 v[80:83], v[142:145], v[230:233], v[80:83]
	v_mfma_f32_16x16x32_bf16 v[126:129], v[146:149], v[182:185], v[126:129]
	v_mfma_f32_16x16x32_bf16 v[122:125], v[154:157], v[182:185], v[122:125]
	v_mfma_f32_16x16x32_bf16 v[110:113], v[146:149], v[190:193], v[110:113]
	v_mfma_f32_16x16x32_bf16 v[106:109], v[154:157], v[190:193], v[106:109]
	v_mfma_f32_16x16x32_bf16 v[92:95], v[146:149], v[218:221], v[92:95]
	v_mfma_f32_16x16x32_bf16 v[88:91], v[154:157], v[218:221], v[88:91]
	v_mfma_f32_16x16x32_bf16 v[76:79], v[146:149], v[226:229], v[76:79]
	v_mfma_f32_16x16x32_bf16 v[72:75], v[154:157], v[226:229], v[72:75]
	v_mfma_f32_16x16x32_bf16 v[126:129], v[150:153], v[186:189], v[126:129]
	v_mfma_f32_16x16x32_bf16 v[122:125], v[170:173], v[186:189], v[122:125]
	v_mfma_f32_16x16x32_bf16 v[110:113], v[150:153], v[214:217], v[110:113]
	v_mfma_f32_16x16x32_bf16 v[106:109], v[170:173], v[214:217], v[106:109]
	v_mfma_f32_16x16x32_bf16 v[92:95], v[150:153], v[222:225], v[92:95]
	v_mfma_f32_16x16x32_bf16 v[88:91], v[170:173], v[222:225], v[88:91]
	v_mfma_f32_16x16x32_bf16 v[76:79], v[150:153], v[230:233], v[76:79]
	v_mfma_f32_16x16x32_bf16 v[72:75], v[170:173], v[230:233], v[72:75]
	s_setprio 0
	s_barrier
	s_add_i32 s3, s3, s74
	v_lshl_add_u64 v[174:175], v[174:175], 0, s[30:31]
	s_mov_b32 m0, s3
	ds_read_b128 v[182:185], v177 offset:49152
	ds_read_b128 v[186:189], v177 offset:50176
	ds_read_b128 v[190:193], v177 offset:51200
	ds_read_b128 v[214:217], v177 offset:52224
	ds_read_b128 v[218:221], v177 offset:53248
	ds_read_b128 v[222:225], v177 offset:54272
	ds_read_b128 v[226:229], v177 offset:55296
	ds_read_b128 v[230:233], v177 offset:56320
	global_load_lds_dwordx4 v[174:175], off
	s_add_i32 m0, s3, 0x2000
	s_add_u32 s6, s24, 0x20080
	v_lshl_add_u64 v[174:175], v[178:179], 0, s[30:31]
	s_addc_u32 s7, s25, 0
	s_add_i32 s3, s18, s74
	global_load_lds_dwordx4 v[174:175], off
	v_lshl_add_u64 v[174:175], s[6:7], 0, v[160:161]
	s_mov_b32 m0, s3
	s_nop 0
	global_load_lds_dwordx4 v[174:175], off
	v_lshl_add_u64 v[174:175], s[6:7], 0, v[164:165]
	s_add_i32 m0, s3, 0x2000
	s_nop 0
	global_load_lds_dwordx4 v[174:175], off
	v_lshl_add_u64 v[174:175], v[180:181], 0, s[30:31]
	s_mov_b32 m0, s97
	s_nop 0
	global_load_lds_dwordx4 v[174:175], off
	v_lshl_add_u64 v[174:175], v[194:195], 0, s[30:31]
	s_mov_b32 m0, s50
	s_nop 0
	global_load_lds_dwordx4 v[174:175], off
	s_setprio 1
	s_waitcnt vmcnt(8)
	s_waitcnt lgkmcnt(0)
	s_barrier
	v_mfma_f32_16x16x32_bf16 v[68:71], v[56:59], v[182:185], v[68:71]
	v_mfma_f32_16x16x32_bf16 v[64:67], v[138:141], v[182:185], v[64:67]
	v_mfma_f32_16x16x32_bf16 v[44:47], v[56:59], v[190:193], v[44:47]
	v_mfma_f32_16x16x32_bf16 v[40:43], v[138:141], v[190:193], v[40:43]
	v_mfma_f32_16x16x32_bf16 v[28:31], v[56:59], v[218:221], v[28:31]
	v_mfma_f32_16x16x32_bf16 v[24:27], v[138:141], v[218:221], v[24:27]
	v_mfma_f32_16x16x32_bf16 v[12:15], v[56:59], v[226:229], v[12:15]
	v_mfma_f32_16x16x32_bf16 v[8:11], v[138:141], v[226:229], v[8:11]
	v_mfma_f32_16x16x32_bf16 v[68:71], v[60:63], v[186:189], v[68:71]
	v_mfma_f32_16x16x32_bf16 v[64:67], v[142:145], v[186:189], v[64:67]
	v_mfma_f32_16x16x32_bf16 v[44:47], v[60:63], v[214:217], v[44:47]
	v_mfma_f32_16x16x32_bf16 v[40:43], v[142:145], v[214:217], v[40:43]
	v_mfma_f32_16x16x32_bf16 v[28:31], v[60:63], v[222:225], v[28:31]
	v_mfma_f32_16x16x32_bf16 v[24:27], v[142:145], v[222:225], v[24:27]
	v_mfma_f32_16x16x32_bf16 v[12:15], v[60:63], v[230:233], v[12:15]
	v_mfma_f32_16x16x32_bf16 v[8:11], v[142:145], v[230:233], v[8:11]
	v_mfma_f32_16x16x32_bf16 v[52:55], v[146:149], v[182:185], v[52:55]
	v_mfma_f32_16x16x32_bf16 v[48:51], v[154:157], v[182:185], v[48:51]
	v_mfma_f32_16x16x32_bf16 v[36:39], v[146:149], v[190:193], v[36:39]
	v_mfma_f32_16x16x32_bf16 v[32:35], v[154:157], v[190:193], v[32:35]
	v_mfma_f32_16x16x32_bf16 v[20:23], v[146:149], v[218:221], v[20:23]
	v_mfma_f32_16x16x32_bf16 v[16:19], v[154:157], v[218:221], v[16:19]
	v_mfma_f32_16x16x32_bf16 v[4:7], v[146:149], v[226:229], v[4:7]
	v_mfma_f32_16x16x32_bf16 v[0:3], v[154:157], v[226:229], v[0:3]
	v_mfma_f32_16x16x32_bf16 v[52:55], v[150:153], v[186:189], v[52:55]
	v_mfma_f32_16x16x32_bf16 v[48:51], v[170:173], v[186:189], v[48:51]
	v_mfma_f32_16x16x32_bf16 v[36:39], v[150:153], v[214:217], v[36:39]
	v_mfma_f32_16x16x32_bf16 v[32:35], v[170:173], v[214:217], v[32:35]
	v_mfma_f32_16x16x32_bf16 v[20:23], v[150:153], v[222:225], v[20:23]
	v_mfma_f32_16x16x32_bf16 v[16:19], v[170:173], v[222:225], v[16:19]
	v_mfma_f32_16x16x32_bf16 v[4:7], v[150:153], v[230:233], v[4:7]
	v_mfma_f32_16x16x32_bf16 v[0:3], v[170:173], v[230:233], v[0:3]
	s_setprio 0
	s_barrier
	s_add_i32 s2, s2, 2
	s_add_u32 s22, s22, 0x100
	s_addc_u32 s23, s23, 0
	s_add_u32 s15, s15, 0x100
	s_addc_u32 s17, s17, 0
	s_cmp_gt_u32 s2, 5
	s_cbranch_scc0 .LBB0_421
	s_nop 0
	s_nop 0
	s_nop 0
	s_nop 0
	s_nop 0
	s_nop 0
	s_nop 0
	s_nop 0
	s_nop 0
	s_nop 0
	s_nop 0
	s_nop 0
	s_and_b64 vcc, exec, s[58:59]
	s_cbranch_vccz .LBB0_424
	s_barrier

.LBB0_717:
	s_add_u32 s3, s42, 0xfffe0080
	s_addc_u32 s6, s43, -1
	s_add_i32 s7, 0, 0x10000
	s_cmp_eq_u32 s2, 4
	s_cselect_b32 s47, s23, s6
	s_cselect_b32 s46, s51, s3
	v_add_u32_e32 v140, s7, v143
	s_cselect_b32 s45, s15, s54
	s_cselect_b32 s44, s52, s53
	s_add_i32 s3, 0, 0x14000
	ds_read_b128 v[146:149], v140
	ds_read_b128 v[150:153], v140 offset:1024
	ds_read_b128 v[154:157], v140 offset:2048
	ds_read_b128 v[158:161], v140 offset:3072
	v_add_u32_e32 v140, s3, v143
	ds_read_b128 v[162:165], v140
	ds_read_b128 v[166:169], v140 offset:1024
	ds_read_b128 v[170:173], v140 offset:2048
	ds_read_b128 v[174:177], v140 offset:3072
	v_lshl_add_u64 v[140:141], s[42:43], 0, v[136:137]
	s_add_i32 m0, s20, 0xc000
	ds_read_b128 v[178:181], v145
	ds_read_b128 v[182:185], v145 offset:1024
	ds_read_b128 v[186:189], v145 offset:2048
	ds_read_b128 v[190:193], v145 offset:3072
	ds_read_b128 v[202:205], v145 offset:4096
	ds_read_b128 v[206:209], v145 offset:5120
	ds_read_b128 v[214:217], v145 offset:6144
	ds_read_b128 v[218:221], v145 offset:7168
	global_load_lds_dwordx4 v[140:141], off
	v_lshl_add_u64 v[140:141], s[42:43], 0, v[138:139]
	s_add_i32 m0, s20, 0xe000
	s_nop 0
	global_load_lds_dwordx4 v[140:141], off
	s_setprio 1
	s_waitcnt vmcnt(8)
	s_waitcnt lgkmcnt(0)
	s_barrier
	v_mfma_f32_16x16x32_bf16 v[126:129], v[146:149], v[178:181], v[126:129]
	v_mfma_f32_16x16x32_bf16 v[122:125], v[154:157], v[178:181], v[122:125]
	v_mfma_f32_16x16x32_bf16 v[118:121], v[146:149], v[186:189], v[118:121]
	v_mfma_f32_16x16x32_bf16 v[110:113], v[154:157], v[186:189], v[110:113]
	v_mfma_f32_16x16x32_bf16 v[102:105], v[146:149], v[202:205], v[102:105]
	v_mfma_f32_16x16x32_bf16 v[92:95], v[154:157], v[202:205], v[92:95]
	v_mfma_f32_16x16x32_bf16 v[84:87], v[146:149], v[214:217], v[84:87]
	v_mfma_f32_16x16x32_bf16 v[76:79], v[154:157], v[214:217], v[76:79]
	v_mfma_f32_16x16x32_bf16 v[126:129], v[150:153], v[182:185], v[126:129]
	v_mfma_f32_16x16x32_bf16 v[122:125], v[158:161], v[182:185], v[122:125]
	v_mfma_f32_16x16x32_bf16 v[118:121], v[150:153], v[190:193], v[118:121]
	v_mfma_f32_16x16x32_bf16 v[110:113], v[158:161], v[190:193], v[110:113]
	v_mfma_f32_16x16x32_bf16 v[102:105], v[150:153], v[206:209], v[102:105]
	v_mfma_f32_16x16x32_bf16 v[92:95], v[158:161], v[206:209], v[92:95]
	v_mfma_f32_16x16x32_bf16 v[84:87], v[150:153], v[218:221], v[84:87]
	v_mfma_f32_16x16x32_bf16 v[76:79], v[158:161], v[218:221], v[76:79]
	v_mfma_f32_16x16x32_bf16 v[114:117], v[162:165], v[178:181], v[114:117]
	v_mfma_f32_16x16x32_bf16 v[106:109], v[170:173], v[178:181], v[106:109]
	v_mfma_f32_16x16x32_bf16 v[98:101], v[162:165], v[186:189], v[98:101]
	v_mfma_f32_16x16x32_bf16 v[88:91], v[170:173], v[186:189], v[88:91]
	v_mfma_f32_16x16x32_bf16 v[80:83], v[162:165], v[202:205], v[80:83]
	v_mfma_f32_16x16x32_bf16 v[72:75], v[170:173], v[202:205], v[72:75]
	v_mfma_f32_16x16x32_bf16 v[68:71], v[162:165], v[214:217], v[68:71]
	v_mfma_f32_16x16x32_bf16 v[64:67], v[170:173], v[214:217], v[64:67]
	v_mfma_f32_16x16x32_bf16 v[114:117], v[166:169], v[182:185], v[114:117]
	v_mfma_f32_16x16x32_bf16 v[106:109], v[174:177], v[182:185], v[106:109]
	v_mfma_f32_16x16x32_bf16 v[98:101], v[166:169], v[190:193], v[98:101]
	v_mfma_f32_16x16x32_bf16 v[88:91], v[174:177], v[190:193], v[88:91]
	v_mfma_f32_16x16x32_bf16 v[80:83], v[166:169], v[206:209], v[80:83]
	v_mfma_f32_16x16x32_bf16 v[72:75], v[174:177], v[206:209], v[72:75]
	v_mfma_f32_16x16x32_bf16 v[68:71], v[166:169], v[218:221], v[68:71]
	v_mfma_f32_16x16x32_bf16 v[64:67], v[174:177], v[218:221], v[64:67]
	s_setprio 0
	s_barrier
	s_add_i32 s6, s7, s4
	v_lshl_add_u64 v[140:141], s[44:45], 0, v[96:97]
	s_mov_b32 m0, s6
	ds_read_b128 v[178:181], v145 offset:16384
	ds_read_b128 v[182:185], v145 offset:17408
	ds_read_b128 v[186:189], v145 offset:18432
	ds_read_b128 v[190:193], v145 offset:19456
	ds_read_b128 v[202:205], v145 offset:20480
	ds_read_b128 v[206:209], v145 offset:21504
	ds_read_b128 v[214:217], v145 offset:22528
	ds_read_b128 v[218:221], v145 offset:23552
	global_load_lds_dwordx4 v[140:141], off
	s_add_i32 m0, s6, 0x2000
	s_add_u32 s6, s44, 0x20000
	v_lshl_add_u64 v[194:195], s[44:45], 0, v[134:135]
	s_addc_u32 s7, s45, 0
	s_add_i32 s3, s3, s4
	global_load_lds_dwordx4 v[194:195], off
	v_lshl_add_u64 v[198:199], s[6:7], 0, v[96:97]
	s_mov_b32 m0, s3
	v_lshl_add_u64 v[200:201], s[46:47], 0, v[132:133]
	global_load_lds_dwordx4 v[198:199], off
	v_lshl_add_u64 v[198:199], s[6:7], 0, v[134:135]
	s_add_i32 m0, s3, 0x2000
	s_nop 0
	global_load_lds_dwordx4 v[198:199], off
	v_lshl_add_u64 v[198:199], s[46:47], 0, v[130:131]
	s_mov_b32 m0, s20
	s_nop 0
	global_load_lds_dwordx4 v[198:199], off
	s_mov_b32 m0, s25
	s_nop 0
	global_load_lds_dwordx4 v[200:201], off
	s_setprio 1
	s_waitcnt vmcnt(8)
	s_waitcnt lgkmcnt(0)
	s_barrier
	v_mfma_f32_16x16x32_bf16 v[60:63], v[146:149], v[178:181], v[60:63]
	v_mfma_f32_16x16x32_bf16 v[56:59], v[154:157], v[178:181], v[56:59]
	v_mfma_f32_16x16x32_bf16 v[52:55], v[146:149], v[186:189], v[52:55]
	v_mfma_f32_16x16x32_bf16 v[44:47], v[154:157], v[186:189], v[44:47]
	v_mfma_f32_16x16x32_bf16 v[36:39], v[146:149], v[202:205], v[36:39]
	v_mfma_f32_16x16x32_bf16 v[28:31], v[154:157], v[202:205], v[28:31]
	v_mfma_f32_16x16x32_bf16 v[20:23], v[146:149], v[214:217], v[20:23]
	v_mfma_f32_16x16x32_bf16 v[12:15], v[154:157], v[214:217], v[12:15]
	v_mfma_f32_16x16x32_bf16 v[60:63], v[150:153], v[182:185], v[60:63]
	v_mfma_f32_16x16x32_bf16 v[56:59], v[158:161], v[182:185], v[56:59]
	v_mfma_f32_16x16x32_bf16 v[52:55], v[150:153], v[190:193], v[52:55]
	v_mfma_f32_16x16x32_bf16 v[44:47], v[158:161], v[190:193], v[44:47]
	v_mfma_f32_16x16x32_bf16 v[36:39], v[150:153], v[206:209], v[36:39]
	v_mfma_f32_16x16x32_bf16 v[28:31], v[158:161], v[206:209], v[28:31]
	v_mfma_f32_16x16x32_bf16 v[20:23], v[150:153], v[218:221], v[20:23]
	v_mfma_f32_16x16x32_bf16 v[12:15], v[158:161], v[218:221], v[12:15]
	v_mfma_f32_16x16x32_bf16 v[48:51], v[162:165], v[178:181], v[48:51]
	v_mfma_f32_16x16x32_bf16 v[40:43], v[170:173], v[178:181], v[40:43]
	v_mfma_f32_16x16x32_bf16 v[32:35], v[162:165], v[186:189], v[32:35]
	v_mfma_f32_16x16x32_bf16 v[24:27], v[170:173], v[186:189], v[24:27]
	v_mfma_f32_16x16x32_bf16 v[16:19], v[162:165], v[202:205], v[16:19]
	v_mfma_f32_16x16x32_bf16 v[8:11], v[170:173], v[202:205], v[8:11]
	v_mfma_f32_16x16x32_bf16 v[4:7], v[162:165], v[214:217], v[4:7]
	v_mfma_f32_16x16x32_bf16 v[0:3], v[170:173], v[214:217], v[0:3]
	v_mfma_f32_16x16x32_bf16 v[48:51], v[166:169], v[182:185], v[48:51]
	v_mfma_f32_16x16x32_bf16 v[40:43], v[174:177], v[182:185], v[40:43]
	v_mfma_f32_16x16x32_bf16 v[32:35], v[166:169], v[190:193], v[32:35]
	v_mfma_f32_16x16x32_bf16 v[24:27], v[174:177], v[190:193], v[24:27]
	v_mfma_f32_16x16x32_bf16 v[16:19], v[166:169], v[206:209], v[16:19]
	v_mfma_f32_16x16x32_bf16 v[8:11], v[174:177], v[206:209], v[8:11]
	v_mfma_f32_16x16x32_bf16 v[4:7], v[166:169], v[218:221], v[4:7]
	v_mfma_f32_16x16x32_bf16 v[0:3], v[174:177], v[218:221], v[0:3]
	s_setprio 0
	s_barrier
	s_add_i32 s3, 0, 0x18000
	s_add_i32 s55, 0, 0x1c000
	v_add_u32_e32 v158, s3, v143
	v_add_u32_e32 v174, s55, v143
	ds_read_b128 v[146:149], v158
	ds_read_b128 v[150:153], v158 offset:1024
	ds_read_b128 v[154:157], v158 offset:2048
	ds_read_b128 v[158:161], v158 offset:3072
	ds_read_b128 v[162:165], v174
	ds_read_b128 v[166:169], v174 offset:1024
	ds_read_b128 v[170:173], v174 offset:2048
	ds_read_b128 v[174:177], v174 offset:3072
	s_add_u32 s6, s46, 0x20000
	s_addc_u32 s7, s47, 0
	s_mov_b32 m0, s36
	v_lshl_add_u64 v[222:223], s[6:7], 0, v[130:131]
	ds_read_b128 v[178:181], v145 offset:32768
	ds_read_b128 v[182:185], v145 offset:33792
	ds_read_b128 v[186:189], v145 offset:34816
	ds_read_b128 v[190:193], v145 offset:35840
	ds_read_b128 v[202:205], v145 offset:36864
	ds_read_b128 v[206:209], v145 offset:37888
	ds_read_b128 v[214:217], v145 offset:38912
	ds_read_b128 v[218:221], v145 offset:39936
	global_load_lds_dwordx4 v[222:223], off
	v_lshl_add_u64 v[222:223], s[6:7], 0, v[132:133]
	s_mov_b32 m0, s37
	s_nop 0
	global_load_lds_dwordx4 v[222:223], off
	s_setprio 1
	s_waitcnt vmcnt(8)
	s_waitcnt lgkmcnt(0)
	s_barrier
	v_mfma_f32_16x16x32_bf16 v[126:129], v[146:149], v[178:181], v[126:129]
	v_mfma_f32_16x16x32_bf16 v[122:125], v[154:157], v[178:181], v[122:125]
	v_mfma_f32_16x16x32_bf16 v[118:121], v[146:149], v[186:189], v[118:121]
	v_mfma_f32_16x16x32_bf16 v[110:113], v[154:157], v[186:189], v[110:113]
	v_mfma_f32_16x16x32_bf16 v[102:105], v[146:149], v[202:205], v[102:105]
	v_mfma_f32_16x16x32_bf16 v[92:95], v[154:157], v[202:205], v[92:95]
	v_mfma_f32_16x16x32_bf16 v[84:87], v[146:149], v[214:217], v[84:87]
	v_mfma_f32_16x16x32_bf16 v[76:79], v[154:157], v[214:217], v[76:79]
	v_mfma_f32_16x16x32_bf16 v[126:129], v[150:153], v[182:185], v[126:129]
	v_mfma_f32_16x16x32_bf16 v[122:125], v[158:161], v[182:185], v[122:125]
	v_mfma_f32_16x16x32_bf16 v[118:121], v[150:153], v[190:193], v[118:121]
	v_mfma_f32_16x16x32_bf16 v[110:113], v[158:161], v[190:193], v[110:113]
	v_mfma_f32_16x16x32_bf16 v[102:105], v[150:153], v[206:209], v[102:105]
	v_mfma_f32_16x16x32_bf16 v[92:95], v[158:161], v[206:209], v[92:95]
	v_mfma_f32_16x16x32_bf16 v[84:87], v[150:153], v[218:221], v[84:87]
	v_mfma_f32_16x16x32_bf16 v[76:79], v[158:161], v[218:221], v[76:79]
	v_mfma_f32_16x16x32_bf16 v[114:117], v[162:165], v[178:181], v[114:117]
	v_mfma_f32_16x16x32_bf16 v[106:109], v[170:173], v[178:181], v[106:109]
	v_mfma_f32_16x16x32_bf16 v[98:101], v[162:165], v[186:189], v[98:101]
	v_mfma_f32_16x16x32_bf16 v[88:91], v[170:173], v[186:189], v[88:91]
	v_mfma_f32_16x16x32_bf16 v[80:83], v[162:165], v[202:205], v[80:83]
	v_mfma_f32_16x16x32_bf16 v[72:75], v[170:173], v[202:205], v[72:75]
	v_mfma_f32_16x16x32_bf16 v[68:71], v[162:165], v[214:217], v[68:71]
	v_mfma_f32_16x16x32_bf16 v[64:67], v[170:173], v[214:217], v[64:67]
	v_mfma_f32_16x16x32_bf16 v[114:117], v[166:169], v[182:185], v[114:117]
	v_mfma_f32_16x16x32_bf16 v[106:109], v[174:177], v[182:185], v[106:109]
	v_mfma_f32_16x16x32_bf16 v[98:101], v[166:169], v[190:193], v[98:101]
	v_mfma_f32_16x16x32_bf16 v[88:91], v[174:177], v[190:193], v[88:91]
	v_mfma_f32_16x16x32_bf16 v[80:83], v[166:169], v[206:209], v[80:83]
	v_mfma_f32_16x16x32_bf16 v[72:75], v[174:177], v[206:209], v[72:75]
	v_mfma_f32_16x16x32_bf16 v[68:71], v[166:169], v[218:221], v[68:71]
	v_mfma_f32_16x16x32_bf16 v[64:67], v[174:177], v[218:221], v[64:67]
	s_setprio 0
	s_barrier
	s_add_i32 s3, s3, s4
	v_lshl_add_u64 v[140:141], v[140:141], 0, s[30:31]
	s_mov_b32 m0, s3
	ds_read_b128 v[178:181], v145 offset:49152
	ds_read_b128 v[182:185], v145 offset:50176
	ds_read_b128 v[186:189], v145 offset:51200
	ds_read_b128 v[190:193], v145 offset:52224
	ds_read_b128 v[202:205], v145 offset:53248
	ds_read_b128 v[206:209], v145 offset:54272
	ds_read_b128 v[214:217], v145 offset:55296
	ds_read_b128 v[218:221], v145 offset:56320
	global_load_lds_dwordx4 v[140:141], off
	s_add_i32 m0, s3, 0x2000
	s_add_u32 s6, s44, 0x20080
	v_lshl_add_u64 v[140:141], v[194:195], 0, s[30:31]
	s_addc_u32 s7, s45, 0
	s_add_i32 s3, s55, s4
	global_load_lds_dwordx4 v[140:141], off
	v_lshl_add_u64 v[140:141], s[6:7], 0, v[96:97]
	s_mov_b32 m0, s3
	s_nop 0
	global_load_lds_dwordx4 v[140:141], off
	v_lshl_add_u64 v[140:141], s[6:7], 0, v[134:135]
	s_add_i32 m0, s3, 0x2000
	s_nop 0
	global_load_lds_dwordx4 v[140:141], off
	v_lshl_add_u64 v[140:141], v[198:199], 0, s[30:31]
	s_mov_b32 m0, s40
	s_nop 0
	global_load_lds_dwordx4 v[140:141], off
	v_lshl_add_u64 v[140:141], v[200:201], 0, s[30:31]
	s_mov_b32 m0, s48
	s_nop 0
	global_load_lds_dwordx4 v[140:141], off
	s_setprio 1
	s_waitcnt vmcnt(8)
	s_waitcnt lgkmcnt(0)
	s_barrier
	v_mfma_f32_16x16x32_bf16 v[60:63], v[146:149], v[178:181], v[60:63]
	v_mfma_f32_16x16x32_bf16 v[56:59], v[154:157], v[178:181], v[56:59]
	v_mfma_f32_16x16x32_bf16 v[52:55], v[146:149], v[186:189], v[52:55]
	v_mfma_f32_16x16x32_bf16 v[44:47], v[154:157], v[186:189], v[44:47]
	v_mfma_f32_16x16x32_bf16 v[36:39], v[146:149], v[202:205], v[36:39]
	v_mfma_f32_16x16x32_bf16 v[28:31], v[154:157], v[202:205], v[28:31]
	v_mfma_f32_16x16x32_bf16 v[20:23], v[146:149], v[214:217], v[20:23]
	v_mfma_f32_16x16x32_bf16 v[12:15], v[154:157], v[214:217], v[12:15]
	v_mfma_f32_16x16x32_bf16 v[60:63], v[150:153], v[182:185], v[60:63]
	v_mfma_f32_16x16x32_bf16 v[56:59], v[158:161], v[182:185], v[56:59]
	v_mfma_f32_16x16x32_bf16 v[52:55], v[150:153], v[190:193], v[52:55]
	v_mfma_f32_16x16x32_bf16 v[44:47], v[158:161], v[190:193], v[44:47]
	v_mfma_f32_16x16x32_bf16 v[36:39], v[150:153], v[206:209], v[36:39]
	v_mfma_f32_16x16x32_bf16 v[28:31], v[158:161], v[206:209], v[28:31]
	v_mfma_f32_16x16x32_bf16 v[20:23], v[150:153], v[218:221], v[20:23]
	v_mfma_f32_16x16x32_bf16 v[12:15], v[158:161], v[218:221], v[12:15]
	v_mfma_f32_16x16x32_bf16 v[48:51], v[162:165], v[178:181], v[48:51]
	v_mfma_f32_16x16x32_bf16 v[40:43], v[170:173], v[178:181], v[40:43]
	v_mfma_f32_16x16x32_bf16 v[32:35], v[162:165], v[186:189], v[32:35]
	v_mfma_f32_16x16x32_bf16 v[24:27], v[170:173], v[186:189], v[24:27]
	v_mfma_f32_16x16x32_bf16 v[16:19], v[162:165], v[202:205], v[16:19]
	v_mfma_f32_16x16x32_bf16 v[8:11], v[170:173], v[202:205], v[8:11]
	v_mfma_f32_16x16x32_bf16 v[4:7], v[162:165], v[214:217], v[4:7]
	v_mfma_f32_16x16x32_bf16 v[0:3], v[170:173], v[214:217], v[0:3]
	v_mfma_f32_16x16x32_bf16 v[48:51], v[166:169], v[182:185], v[48:51]
	v_mfma_f32_16x16x32_bf16 v[40:43], v[174:177], v[182:185], v[40:43]
	v_mfma_f32_16x16x32_bf16 v[32:35], v[166:169], v[190:193], v[32:35]
	v_mfma_f32_16x16x32_bf16 v[24:27], v[174:177], v[190:193], v[24:27]
	v_mfma_f32_16x16x32_bf16 v[16:19], v[166:169], v[206:209], v[16:19]
	v_mfma_f32_16x16x32_bf16 v[8:11], v[174:177], v[206:209], v[8:11]
	v_mfma_f32_16x16x32_bf16 v[4:7], v[166:169], v[218:221], v[4:7]
	v_mfma_f32_16x16x32_bf16 v[0:3], v[174:177], v[218:221], v[0:3]
	s_setprio 0
	s_barrier
	s_add_i32 s2, s2, 2
	s_add_u32 s42, s42, 0x100
	s_addc_u32 s43, s43, 0
	s_add_u32 s53, s53, 0x100
	s_addc_u32 s54, s54, 0
	s_cmp_gt_u32 s2, 5
	s_cbranch_scc0 .LBB0_717
	s_nop 0
	s_nop 0
	s_nop 0
	s_nop 0
	s_nop 0
	s_nop 0
	s_nop 0
	s_nop 0
	s_nop 0
	s_nop 0
	s_nop 0
	s_nop 0
	v_readlane_b32 s54, v254, 56
	s_and_b64 vcc, exec, s[10:11]
	v_readlane_b32 s55, v254, 57
	s_cbranch_vccz .LBB0_720
	s_barrier

.LBB0_993:
	s_add_u32 s3, s24, s46
	s_addc_u32 s6, s25, s47
	s_add_u32 s3, s3, 0x100
	s_addc_u32 s6, s6, 0
	s_add_u32 s48, s59, s46
	s_addc_u32 s49, s60, s47
	s_add_i32 s63, 0, 0x10000
	s_cmpk_eq_i32 s46, 0xf00
	s_cselect_b32 s51, s23, s6
	s_cselect_b32 s50, s61, s3
	v_add_u32_e32 v146, s63, v144
	s_cselect_b32 s49, s15, s49
	s_cselect_b32 s48, s62, s48
	s_add_i32 s3, 0, 0x14000
	ds_read_b128 v[154:157], v146
	ds_read_b128 v[158:161], v146 offset:1024
	ds_read_b128 v[162:165], v146 offset:2048
	ds_read_b128 v[166:169], v146 offset:3072
	v_add_u32_e32 v146, s3, v144
	ds_read_b128 v[174:177], v146
	ds_read_b128 v[178:181], v146 offset:1024
	ds_read_b128 v[182:185], v146 offset:2048
	ds_read_b128 v[186:189], v146 offset:3072
	v_lshl_add_u64 v[146:147], v[140:141], 0, s[46:47]
	s_add_i32 m0, s17, 0xc000
	ds_read_b128 v[190:193], v145
	ds_read_b128 v[202:205], v145 offset:1024
	ds_read_b128 v[206:209], v145 offset:2048
	ds_read_b128 v[214:217], v145 offset:3072
	ds_read_b128 v[218:221], v145 offset:4096
	ds_read_b128 v[222:225], v145 offset:5120
	ds_read_b128 v[226:229], v145 offset:6144
	ds_read_b128 v[230:233], v145 offset:7168
	global_load_lds_dwordx4 v[146:147], off
	v_lshl_add_u64 v[146:147], v[142:143], 0, s[46:47]
	s_add_i32 m0, s17, 0xe000
	s_nop 0
	global_load_lds_dwordx4 v[146:147], off
	s_setprio 1
	s_waitcnt vmcnt(8)
	s_waitcnt lgkmcnt(0)
	s_barrier
	v_mfma_f32_16x16x32_bf16 v[110:113], v[154:157], v[190:193], v[110:113]
	v_mfma_f32_16x16x32_bf16 v[106:109], v[162:165], v[190:193], v[106:109]
	v_mfma_f32_16x16x32_bf16 v[118:121], v[154:157], v[206:209], v[118:121]
	v_mfma_f32_16x16x32_bf16 v[114:117], v[162:165], v[206:209], v[114:117]
	v_mfma_f32_16x16x32_bf16 v[126:129], v[154:157], v[218:221], v[126:129]
	v_mfma_f32_16x16x32_bf16 v[122:125], v[162:165], v[218:221], v[122:125]
	v_mfma_f32_16x16x32_bf16 v[92:95], v[154:157], v[226:229], v[92:95]
	v_mfma_f32_16x16x32_bf16 v[88:91], v[162:165], v[226:229], v[88:91]
	v_mfma_f32_16x16x32_bf16 v[110:113], v[158:161], v[202:205], v[110:113]
	v_mfma_f32_16x16x32_bf16 v[106:109], v[166:169], v[202:205], v[106:109]
	v_mfma_f32_16x16x32_bf16 v[118:121], v[158:161], v[214:217], v[118:121]
	v_mfma_f32_16x16x32_bf16 v[114:117], v[166:169], v[214:217], v[114:117]
	v_mfma_f32_16x16x32_bf16 v[126:129], v[158:161], v[222:225], v[126:129]
	v_mfma_f32_16x16x32_bf16 v[122:125], v[166:169], v[222:225], v[122:125]
	v_mfma_f32_16x16x32_bf16 v[92:95], v[158:161], v[230:233], v[92:95]
	v_mfma_f32_16x16x32_bf16 v[88:91], v[166:169], v[230:233], v[88:91]
	v_mfma_f32_16x16x32_bf16 v[4:7], v[174:177], v[190:193], v[4:7]
	v_mfma_f32_16x16x32_bf16 v[0:3], v[182:185], v[190:193], v[0:3]
	v_mfma_f32_16x16x32_bf16 v[12:15], v[174:177], v[206:209], v[12:15]
	v_mfma_f32_16x16x32_bf16 v[8:11], v[182:185], v[206:209], v[8:11]
	v_mfma_f32_16x16x32_bf16 v[24:27], v[174:177], v[218:221], v[24:27]
	v_mfma_f32_16x16x32_bf16 v[20:23], v[182:185], v[218:221], v[20:23]
	v_mfma_f32_16x16x32_bf16 v[40:43], v[174:177], v[226:229], v[40:43]
	v_mfma_f32_16x16x32_bf16 v[32:35], v[182:185], v[226:229], v[32:35]
	v_mfma_f32_16x16x32_bf16 v[4:7], v[178:181], v[202:205], v[4:7]
	v_mfma_f32_16x16x32_bf16 v[0:3], v[186:189], v[202:205], v[0:3]
	v_mfma_f32_16x16x32_bf16 v[12:15], v[178:181], v[214:217], v[12:15]
	v_mfma_f32_16x16x32_bf16 v[8:11], v[186:189], v[214:217], v[8:11]
	v_mfma_f32_16x16x32_bf16 v[24:27], v[178:181], v[222:225], v[24:27]
	v_mfma_f32_16x16x32_bf16 v[20:23], v[186:189], v[222:225], v[20:23]
	v_mfma_f32_16x16x32_bf16 v[40:43], v[178:181], v[230:233], v[40:43]
	v_mfma_f32_16x16x32_bf16 v[32:35], v[186:189], v[230:233], v[32:35]
	s_setprio 0
	s_barrier
	s_add_i32 s6, s63, s5
	v_lshl_add_u64 v[146:147], s[48:49], 0, v[96:97]
	s_mov_b32 m0, s6
	ds_read_b128 v[190:193], v145 offset:16384
	ds_read_b128 v[202:205], v145 offset:17408
	ds_read_b128 v[206:209], v145 offset:18432
	ds_read_b128 v[214:217], v145 offset:19456
	ds_read_b128 v[218:221], v145 offset:20480
	ds_read_b128 v[222:225], v145 offset:21504
	ds_read_b128 v[226:229], v145 offset:22528
	ds_read_b128 v[230:233], v145 offset:23552
	global_load_lds_dwordx4 v[146:147], off
	s_add_i32 m0, s6, 0x2000
	s_add_u32 s72, s48, 0x80000
	v_lshl_add_u64 v[150:151], s[48:49], 0, v[130:131]
	s_addc_u32 s73, s49, 0
	s_add_i32 s3, s3, s5
	global_load_lds_dwordx4 v[150:151], off
	v_lshl_add_u64 v[170:171], s[72:73], 0, v[96:97]
	s_mov_b32 m0, s3
	v_lshl_add_u64 v[194:195], s[50:51], 0, v[132:133]
	global_load_lds_dwordx4 v[170:171], off
	v_lshl_add_u64 v[170:171], s[72:73], 0, v[130:131]
	s_add_i32 m0, s3, 0x2000
	s_nop 0
	global_load_lds_dwordx4 v[170:171], off
	v_lshl_add_u64 v[170:171], s[50:51], 0, v[134:135]
	s_mov_b32 m0, s17
	s_nop 0
	global_load_lds_dwordx4 v[170:171], off
	s_mov_b32 m0, s18
	s_nop 0
	global_load_lds_dwordx4 v[194:195], off
	s_setprio 1
	s_waitcnt vmcnt(8)
	s_waitcnt lgkmcnt(0)
	s_barrier
	v_mfma_f32_16x16x32_bf16 v[102:105], v[154:157], v[190:193], v[102:105]
	v_mfma_f32_16x16x32_bf16 v[98:101], v[162:165], v[190:193], v[98:101]
	v_mfma_f32_16x16x32_bf16 v[84:87], v[154:157], v[206:209], v[84:87]
	v_mfma_f32_16x16x32_bf16 v[80:83], v[162:165], v[206:209], v[80:83]
	v_mfma_f32_16x16x32_bf16 v[68:71], v[154:157], v[218:221], v[68:71]
	v_mfma_f32_16x16x32_bf16 v[64:67], v[162:165], v[218:221], v[64:67]
	v_mfma_f32_16x16x32_bf16 v[44:47], v[154:157], v[226:229], v[44:47]
	v_mfma_f32_16x16x32_bf16 v[36:39], v[162:165], v[226:229], v[36:39]
	v_mfma_f32_16x16x32_bf16 v[102:105], v[158:161], v[202:205], v[102:105]
	v_mfma_f32_16x16x32_bf16 v[98:101], v[166:169], v[202:205], v[98:101]
	v_mfma_f32_16x16x32_bf16 v[84:87], v[158:161], v[214:217], v[84:87]
	v_mfma_f32_16x16x32_bf16 v[80:83], v[166:169], v[214:217], v[80:83]
	v_mfma_f32_16x16x32_bf16 v[68:71], v[158:161], v[222:225], v[68:71]
	v_mfma_f32_16x16x32_bf16 v[64:67], v[166:169], v[222:225], v[64:67]
	v_mfma_f32_16x16x32_bf16 v[44:47], v[158:161], v[230:233], v[44:47]
	v_mfma_f32_16x16x32_bf16 v[36:39], v[166:169], v[230:233], v[36:39]
	v_mfma_f32_16x16x32_bf16 v[60:63], v[174:177], v[190:193], v[60:63]
	v_mfma_f32_16x16x32_bf16 v[56:59], v[182:185], v[190:193], v[56:59]
	v_mfma_f32_16x16x32_bf16 v[76:79], v[174:177], v[206:209], v[76:79]
	v_mfma_f32_16x16x32_bf16 v[72:75], v[182:185], v[206:209], v[72:75]
	v_mfma_f32_16x16x32_bf16 v[52:55], v[174:177], v[218:221], v[52:55]
	v_mfma_f32_16x16x32_bf16 v[48:51], v[182:185], v[218:221], v[48:51]
	v_mfma_f32_16x16x32_bf16 v[28:31], v[174:177], v[226:229], v[28:31]
	v_mfma_f32_16x16x32_bf16 v[16:19], v[182:185], v[226:229], v[16:19]
	v_mfma_f32_16x16x32_bf16 v[60:63], v[178:181], v[202:205], v[60:63]
	v_mfma_f32_16x16x32_bf16 v[56:59], v[186:189], v[202:205], v[56:59]
	v_mfma_f32_16x16x32_bf16 v[76:79], v[178:181], v[214:217], v[76:79]
	v_mfma_f32_16x16x32_bf16 v[72:75], v[186:189], v[214:217], v[72:75]
	v_mfma_f32_16x16x32_bf16 v[52:55], v[178:181], v[222:225], v[52:55]
	v_mfma_f32_16x16x32_bf16 v[48:51], v[186:189], v[222:225], v[48:51]
	v_mfma_f32_16x16x32_bf16 v[28:31], v[178:181], v[230:233], v[28:31]
	v_mfma_f32_16x16x32_bf16 v[16:19], v[186:189], v[230:233], v[16:19]
	s_setprio 0
	s_barrier
	s_add_i32 s3, 0, 0x18000
	v_add_u32_e32 v149, s3, v144
	s_add_i32 s6, 0, 0x1c000
	ds_read_b128 v[154:157], v149
	ds_read_b128 v[158:161], v149 offset:1024
	ds_read_b128 v[162:165], v149 offset:2048
	ds_read_b128 v[166:169], v149 offset:3072
	v_add_u32_e32 v149, s6, v144
	ds_read_b128 v[174:177], v149
	ds_read_b128 v[178:181], v149 offset:1024
	ds_read_b128 v[182:185], v149 offset:2048
	ds_read_b128 v[186:189], v149 offset:3072
	s_add_u32 s50, s50, 0x80000
	s_addc_u32 s51, s51, 0
	s_mov_b32 m0, s19
	v_lshl_add_u64 v[198:199], s[50:51], 0, v[134:135]
	ds_read_b128 v[190:193], v145 offset:32768
	ds_read_b128 v[202:205], v145 offset:33792
	ds_read_b128 v[206:209], v145 offset:34816
	ds_read_b128 v[214:217], v145 offset:35840
	ds_read_b128 v[218:221], v145 offset:36864
	ds_read_b128 v[222:225], v145 offset:37888
	ds_read_b128 v[226:229], v145 offset:38912
	ds_read_b128 v[230:233], v145 offset:39936
	global_load_lds_dwordx4 v[198:199], off
	v_lshl_add_u64 v[198:199], s[50:51], 0, v[132:133]
	s_mov_b32 m0, s20
	s_nop 0
	global_load_lds_dwordx4 v[198:199], off
	s_setprio 1
	s_waitcnt vmcnt(8)
	s_waitcnt lgkmcnt(0)
	s_barrier
	v_mfma_f32_16x16x32_bf16 v[110:113], v[154:157], v[190:193], v[110:113]
	v_mfma_f32_16x16x32_bf16 v[106:109], v[162:165], v[190:193], v[106:109]
	v_mfma_f32_16x16x32_bf16 v[118:121], v[154:157], v[206:209], v[118:121]
	v_mfma_f32_16x16x32_bf16 v[114:117], v[162:165], v[206:209], v[114:117]
	v_mfma_f32_16x16x32_bf16 v[126:129], v[154:157], v[218:221], v[126:129]
	v_mfma_f32_16x16x32_bf16 v[122:125], v[162:165], v[218:221], v[122:125]
	v_mfma_f32_16x16x32_bf16 v[92:95], v[154:157], v[226:229], v[92:95]
	v_mfma_f32_16x16x32_bf16 v[88:91], v[162:165], v[226:229], v[88:91]
	v_mfma_f32_16x16x32_bf16 v[110:113], v[158:161], v[202:205], v[110:113]
	v_mfma_f32_16x16x32_bf16 v[106:109], v[166:169], v[202:205], v[106:109]
	v_mfma_f32_16x16x32_bf16 v[118:121], v[158:161], v[214:217], v[118:121]
	v_mfma_f32_16x16x32_bf16 v[114:117], v[166:169], v[214:217], v[114:117]
	v_mfma_f32_16x16x32_bf16 v[126:129], v[158:161], v[222:225], v[126:129]
	v_mfma_f32_16x16x32_bf16 v[122:125], v[166:169], v[222:225], v[122:125]
	v_mfma_f32_16x16x32_bf16 v[92:95], v[158:161], v[230:233], v[92:95]
	v_mfma_f32_16x16x32_bf16 v[88:91], v[166:169], v[230:233], v[88:91]
	v_mfma_f32_16x16x32_bf16 v[4:7], v[174:177], v[190:193], v[4:7]
	v_mfma_f32_16x16x32_bf16 v[0:3], v[182:185], v[190:193], v[0:3]
	v_mfma_f32_16x16x32_bf16 v[12:15], v[174:177], v[206:209], v[12:15]
	v_mfma_f32_16x16x32_bf16 v[8:11], v[182:185], v[206:209], v[8:11]
	v_mfma_f32_16x16x32_bf16 v[24:27], v[174:177], v[218:221], v[24:27]
	v_mfma_f32_16x16x32_bf16 v[20:23], v[182:185], v[218:221], v[20:23]
	v_mfma_f32_16x16x32_bf16 v[40:43], v[174:177], v[226:229], v[40:43]
	v_mfma_f32_16x16x32_bf16 v[32:35], v[182:185], v[226:229], v[32:35]
	v_mfma_f32_16x16x32_bf16 v[4:7], v[178:181], v[202:205], v[4:7]
	v_mfma_f32_16x16x32_bf16 v[0:3], v[186:189], v[202:205], v[0:3]
	v_mfma_f32_16x16x32_bf16 v[12:15], v[178:181], v[214:217], v[12:15]
	v_mfma_f32_16x16x32_bf16 v[8:11], v[186:189], v[214:217], v[8:11]
	v_mfma_f32_16x16x32_bf16 v[24:27], v[178:181], v[222:225], v[24:27]
	v_mfma_f32_16x16x32_bf16 v[20:23], v[186:189], v[222:225], v[20:23]
	v_mfma_f32_16x16x32_bf16 v[40:43], v[178:181], v[230:233], v[40:43]
	v_mfma_f32_16x16x32_bf16 v[32:35], v[186:189], v[230:233], v[32:35]
	s_setprio 0
	s_barrier
	s_add_i32 s3, s3, s5
	v_lshl_add_u64 v[146:147], v[146:147], 0, s[30:31]
	s_mov_b32 m0, s3
	ds_read_b128 v[190:193], v145 offset:49152
	ds_read_b128 v[202:205], v145 offset:50176
	ds_read_b128 v[206:209], v145 offset:51200
	ds_read_b128 v[214:217], v145 offset:52224
	ds_read_b128 v[218:221], v145 offset:53248
	ds_read_b128 v[222:225], v145 offset:54272
	ds_read_b128 v[226:229], v145 offset:55296
	ds_read_b128 v[230:233], v145 offset:56320
	global_load_lds_dwordx4 v[146:147], off
	s_add_i32 m0, s3, 0x2000
	s_add_u32 s48, s48, 0x80080
	v_lshl_add_u64 v[146:147], v[150:151], 0, s[30:31]
	s_addc_u32 s49, s49, 0
	s_add_i32 s3, s6, s5
	global_load_lds_dwordx4 v[146:147], off
	v_lshl_add_u64 v[146:147], s[48:49], 0, v[96:97]
	s_mov_b32 m0, s3
	s_nop 0
	global_load_lds_dwordx4 v[146:147], off
	v_lshl_add_u64 v[146:147], s[48:49], 0, v[130:131]
	s_add_i32 m0, s3, 0x2000
	s_nop 0
	global_load_lds_dwordx4 v[146:147], off
	v_lshl_add_u64 v[146:147], v[170:171], 0, s[30:31]
	s_mov_b32 m0, s37
	s_nop 0
	global_load_lds_dwordx4 v[146:147], off
	v_lshl_add_u64 v[146:147], v[194:195], 0, s[30:31]
	s_mov_b32 m0, s56
	s_nop 0
	global_load_lds_dwordx4 v[146:147], off
	s_setprio 1
	s_waitcnt vmcnt(8)
	s_waitcnt lgkmcnt(0)
	s_barrier
	v_mfma_f32_16x16x32_bf16 v[102:105], v[154:157], v[190:193], v[102:105]
	v_mfma_f32_16x16x32_bf16 v[98:101], v[162:165], v[190:193], v[98:101]
	v_mfma_f32_16x16x32_bf16 v[84:87], v[154:157], v[206:209], v[84:87]
	v_mfma_f32_16x16x32_bf16 v[80:83], v[162:165], v[206:209], v[80:83]
	v_mfma_f32_16x16x32_bf16 v[68:71], v[154:157], v[218:221], v[68:71]
	v_mfma_f32_16x16x32_bf16 v[64:67], v[162:165], v[218:221], v[64:67]
	v_mfma_f32_16x16x32_bf16 v[44:47], v[154:157], v[226:229], v[44:47]
	v_mfma_f32_16x16x32_bf16 v[36:39], v[162:165], v[226:229], v[36:39]
	v_mfma_f32_16x16x32_bf16 v[102:105], v[158:161], v[202:205], v[102:105]
	v_mfma_f32_16x16x32_bf16 v[98:101], v[166:169], v[202:205], v[98:101]
	v_mfma_f32_16x16x32_bf16 v[84:87], v[158:161], v[214:217], v[84:87]
	v_mfma_f32_16x16x32_bf16 v[80:83], v[166:169], v[214:217], v[80:83]
	v_mfma_f32_16x16x32_bf16 v[68:71], v[158:161], v[222:225], v[68:71]
	v_mfma_f32_16x16x32_bf16 v[64:67], v[166:169], v[222:225], v[64:67]
	v_mfma_f32_16x16x32_bf16 v[44:47], v[158:161], v[230:233], v[44:47]
	v_mfma_f32_16x16x32_bf16 v[36:39], v[166:169], v[230:233], v[36:39]
	v_mfma_f32_16x16x32_bf16 v[60:63], v[174:177], v[190:193], v[60:63]
	v_mfma_f32_16x16x32_bf16 v[56:59], v[182:185], v[190:193], v[56:59]
	v_mfma_f32_16x16x32_bf16 v[76:79], v[174:177], v[206:209], v[76:79]
	v_mfma_f32_16x16x32_bf16 v[72:75], v[182:185], v[206:209], v[72:75]
	v_mfma_f32_16x16x32_bf16 v[52:55], v[174:177], v[218:221], v[52:55]
	v_mfma_f32_16x16x32_bf16 v[48:51], v[182:185], v[218:221], v[48:51]
	v_mfma_f32_16x16x32_bf16 v[28:31], v[174:177], v[226:229], v[28:31]
	v_mfma_f32_16x16x32_bf16 v[16:19], v[182:185], v[226:229], v[16:19]
	v_mfma_f32_16x16x32_bf16 v[60:63], v[178:181], v[202:205], v[60:63]
	v_mfma_f32_16x16x32_bf16 v[56:59], v[186:189], v[202:205], v[56:59]
	v_mfma_f32_16x16x32_bf16 v[76:79], v[178:181], v[214:217], v[76:79]
	v_mfma_f32_16x16x32_bf16 v[72:75], v[186:189], v[214:217], v[72:75]
	v_mfma_f32_16x16x32_bf16 v[52:55], v[178:181], v[222:225], v[52:55]
	v_mfma_f32_16x16x32_bf16 v[48:51], v[186:189], v[222:225], v[48:51]
	v_mfma_f32_16x16x32_bf16 v[28:31], v[178:181], v[230:233], v[28:31]
	v_mfma_f32_16x16x32_bf16 v[16:19], v[186:189], v[230:233], v[16:19]
	s_setprio 0
	s_barrier
	s_add_i32 s2, s2, 2
	s_add_u32 s46, s46, 0x100
	s_addc_u32 s47, s47, 0
	s_cmp_gt_u32 s2, 29
	s_cbranch_scc0 .LBB0_993
	s_nop 0
	s_nop 0
	s_nop 0
	s_nop 0
	s_nop 0
	s_nop 0
	s_nop 0
	s_nop 0
	s_nop 0
	s_nop 0
	s_nop 0
	s_nop 0
	s_and_b64 vcc, exec, s[12:13]
	s_cbranch_vccz .LBB0_996
	s_barrier

.LBB0_1158:
	s_add_u32 s34, s62, 0x100
	s_addc_u32 s35, s63, 0
	s_add_i32 s67, 0, 0x10000
	s_cmp_eq_u32 s6, 28
	s_cselect_b32 s89, s23, s35
	s_cselect_b32 s88, s61, s34
	s_cselect_b32 vcc_hi, s91, s3
	s_cselect_b32 vcc_lo, s93, s2
	s_add_i32 s76, 0, 0x14000
	v_add_u32_e32 v142, s67, v191
	v_add_u32_e32 v158, s76, v191
	ds_read_b128 v[130:133], v142
	ds_read_b128 v[134:137], v142 offset:1024
	ds_read_b128 v[138:141], v142 offset:2048
	ds_read_b128 v[142:145], v142 offset:3072
	ds_read_b128 v[146:149], v158
	ds_read_b128 v[150:153], v158 offset:1024
	ds_read_b128 v[154:157], v158 offset:2048
	ds_read_b128 v[158:161], v158 offset:3072
	v_lshl_add_u64 v[188:189], s[62:63], 0, v[184:185]
	s_add_i32 m0, s17, 0xc000
	ds_read_b128 v[162:165], v224
	ds_read_b128 v[166:169], v224 offset:1024
	ds_read_b128 v[170:173], v224 offset:2048
	ds_read_b128 v[178:181], v224 offset:3072
	ds_read_b128 v[202:205], v224 offset:4096
	ds_read_b128 v[206:209], v224 offset:5120
	ds_read_b128 v[226:229], v224 offset:6144
	ds_read_b128 v[230:233], v224 offset:7168
	global_load_lds_dwordx4 v[188:189], off
	v_lshl_add_u64 v[188:189], s[62:63], 0, v[186:187]
	s_add_i32 m0, s17, 0xe000
	s_nop 0
	global_load_lds_dwordx4 v[188:189], off
	s_setprio 1
	s_waitcnt vmcnt(8)
	s_waitcnt lgkmcnt(0)
	s_barrier
	v_mfma_f32_16x16x32_bf16 v[126:129], v[130:133], v[162:165], v[126:129]
	v_mfma_f32_16x16x32_bf16 v[56:59], v[138:141], v[162:165], v[56:59]
	v_mfma_f32_16x16x32_bf16 v[122:125], v[130:133], v[170:173], v[122:125]
	v_mfma_f32_16x16x32_bf16 v[52:55], v[138:141], v[170:173], v[52:55]
	v_mfma_f32_16x16x32_bf16 v[118:121], v[130:133], v[202:205], v[118:121]
	v_mfma_f32_16x16x32_bf16 v[60:63], v[138:141], v[202:205], v[60:63]
	v_mfma_f32_16x16x32_bf16 v[114:117], v[130:133], v[226:229], v[114:117]
	v_mfma_f32_16x16x32_bf16 v[44:47], v[138:141], v[226:229], v[44:47]
	v_mfma_f32_16x16x32_bf16 v[126:129], v[134:137], v[166:169], v[126:129]
	v_mfma_f32_16x16x32_bf16 v[56:59], v[142:145], v[166:169], v[56:59]
	v_mfma_f32_16x16x32_bf16 v[122:125], v[134:137], v[178:181], v[122:125]
	v_mfma_f32_16x16x32_bf16 v[52:55], v[142:145], v[178:181], v[52:55]
	v_mfma_f32_16x16x32_bf16 v[118:121], v[134:137], v[206:209], v[118:121]
	v_mfma_f32_16x16x32_bf16 v[60:63], v[142:145], v[206:209], v[60:63]
	v_mfma_f32_16x16x32_bf16 v[114:117], v[134:137], v[230:233], v[114:117]
	v_mfma_f32_16x16x32_bf16 v[44:47], v[142:145], v[230:233], v[44:47]
	v_mfma_f32_16x16x32_bf16 v[110:113], v[146:149], v[162:165], v[110:113]
	v_mfma_f32_16x16x32_bf16 v[40:43], v[154:157], v[162:165], v[40:43]
	v_mfma_f32_16x16x32_bf16 v[106:109], v[146:149], v[170:173], v[106:109]
	v_mfma_f32_16x16x32_bf16 v[36:39], v[154:157], v[170:173], v[36:39]
	v_mfma_f32_16x16x32_bf16 v[102:105], v[146:149], v[202:205], v[102:105]
	v_mfma_f32_16x16x32_bf16 v[48:51], v[154:157], v[202:205], v[48:51]
	v_mfma_f32_16x16x32_bf16 v[98:101], v[146:149], v[226:229], v[98:101]
	v_mfma_f32_16x16x32_bf16 v[32:35], v[154:157], v[226:229], v[32:35]
	v_mfma_f32_16x16x32_bf16 v[110:113], v[150:153], v[166:169], v[110:113]
	v_mfma_f32_16x16x32_bf16 v[40:43], v[158:161], v[166:169], v[40:43]
	v_mfma_f32_16x16x32_bf16 v[106:109], v[150:153], v[178:181], v[106:109]
	v_mfma_f32_16x16x32_bf16 v[36:39], v[158:161], v[178:181], v[36:39]
	v_mfma_f32_16x16x32_bf16 v[102:105], v[150:153], v[206:209], v[102:105]
	v_mfma_f32_16x16x32_bf16 v[48:51], v[158:161], v[206:209], v[48:51]
	v_mfma_f32_16x16x32_bf16 v[98:101], v[150:153], v[230:233], v[98:101]
	v_mfma_f32_16x16x32_bf16 v[32:35], v[158:161], v[230:233], v[32:35]
	s_setprio 0
	s_barrier
	s_add_i32 s62, s67, s5
	v_lshl_add_u64 v[188:189], vcc, 0, v[96:97]
	s_mov_b32 m0, s62
	ds_read_b128 v[162:165], v224 offset:16384
	ds_read_b128 v[166:169], v224 offset:17408
	ds_read_b128 v[170:173], v224 offset:18432
	ds_read_b128 v[178:181], v224 offset:19456
	ds_read_b128 v[202:205], v224 offset:20480
	ds_read_b128 v[206:209], v224 offset:21504
	ds_read_b128 v[226:229], v224 offset:22528
	ds_read_b128 v[230:233], v224 offset:23552
	global_load_lds_dwordx4 v[188:189], off
	s_add_i32 m0, s62, 0x2000
	s_add_u32 s62, vcc_lo, 0x80000
	v_lshl_add_u64 v[198:199], vcc, 0, v[182:183]
	s_addc_u32 s63, vcc_hi, 0
	s_add_i32 s67, s76, s5
	global_load_lds_dwordx4 v[198:199], off
	v_lshl_add_u64 v[200:201], s[62:63], 0, v[96:97]
	s_mov_b32 m0, s67
	v_lshl_add_u64 v[234:235], s[88:89], 0, v[176:177]
	global_load_lds_dwordx4 v[200:201], off
	v_lshl_add_u64 v[200:201], s[62:63], 0, v[182:183]
	s_add_i32 m0, s67, 0x2000
	s_nop 0
	global_load_lds_dwordx4 v[200:201], off
	v_lshl_add_u64 v[200:201], s[88:89], 0, v[174:175]
	s_mov_b32 m0, s17
	s_nop 0
	global_load_lds_dwordx4 v[200:201], off
	s_mov_b32 m0, s18
	s_nop 0
	global_load_lds_dwordx4 v[234:235], off
	s_setprio 1
	s_waitcnt vmcnt(8)
	s_waitcnt lgkmcnt(0)
	s_barrier
	v_mfma_f32_16x16x32_bf16 v[92:95], v[130:133], v[162:165], v[92:95]
	v_mfma_f32_16x16x32_bf16 v[24:27], v[138:141], v[162:165], v[24:27]
	v_mfma_f32_16x16x32_bf16 v[88:91], v[130:133], v[170:173], v[88:91]
	v_mfma_f32_16x16x32_bf16 v[28:31], v[138:141], v[170:173], v[28:31]
	v_mfma_f32_16x16x32_bf16 v[84:87], v[130:133], v[202:205], v[84:87]
	v_mfma_f32_16x16x32_bf16 v[16:19], v[138:141], v[202:205], v[16:19]
	v_mfma_f32_16x16x32_bf16 v[80:83], v[130:133], v[226:229], v[80:83]
	v_mfma_f32_16x16x32_bf16 v[20:23], v[138:141], v[226:229], v[20:23]
	v_mfma_f32_16x16x32_bf16 v[92:95], v[134:137], v[166:169], v[92:95]
	v_mfma_f32_16x16x32_bf16 v[24:27], v[142:145], v[166:169], v[24:27]
	v_mfma_f32_16x16x32_bf16 v[88:91], v[134:137], v[178:181], v[88:91]
	v_mfma_f32_16x16x32_bf16 v[28:31], v[142:145], v[178:181], v[28:31]
	v_mfma_f32_16x16x32_bf16 v[84:87], v[134:137], v[206:209], v[84:87]
	v_mfma_f32_16x16x32_bf16 v[16:19], v[142:145], v[206:209], v[16:19]
	v_mfma_f32_16x16x32_bf16 v[80:83], v[134:137], v[230:233], v[80:83]
	v_mfma_f32_16x16x32_bf16 v[20:23], v[142:145], v[230:233], v[20:23]
	v_mfma_f32_16x16x32_bf16 v[76:79], v[146:149], v[162:165], v[76:79]
	v_mfma_f32_16x16x32_bf16 v[12:15], v[154:157], v[162:165], v[12:15]
	v_mfma_f32_16x16x32_bf16 v[72:75], v[146:149], v[170:173], v[72:75]
	v_mfma_f32_16x16x32_bf16 v[8:11], v[154:157], v[170:173], v[8:11]
	v_mfma_f32_16x16x32_bf16 v[68:71], v[146:149], v[202:205], v[68:71]
	v_mfma_f32_16x16x32_bf16 v[0:3], v[154:157], v[202:205], v[0:3]
	v_mfma_f32_16x16x32_bf16 v[64:67], v[146:149], v[226:229], v[64:67]
	v_mfma_f32_16x16x32_bf16 v[4:7], v[154:157], v[226:229], v[4:7]
	v_mfma_f32_16x16x32_bf16 v[76:79], v[150:153], v[166:169], v[76:79]
	v_mfma_f32_16x16x32_bf16 v[12:15], v[158:161], v[166:169], v[12:15]
	v_mfma_f32_16x16x32_bf16 v[72:75], v[150:153], v[178:181], v[72:75]
	v_mfma_f32_16x16x32_bf16 v[8:11], v[158:161], v[178:181], v[8:11]
	v_mfma_f32_16x16x32_bf16 v[68:71], v[150:153], v[206:209], v[68:71]
	v_mfma_f32_16x16x32_bf16 v[0:3], v[158:161], v[206:209], v[0:3]
	v_mfma_f32_16x16x32_bf16 v[64:67], v[150:153], v[230:233], v[64:67]
	v_mfma_f32_16x16x32_bf16 v[4:7], v[158:161], v[230:233], v[4:7]
	s_setprio 0
	s_barrier
	s_add_i32 s67, 0, 0x18000
	s_add_i32 s76, 0, 0x1c000
	v_add_u32_e32 v142, s67, v191
	v_add_u32_e32 v158, s76, v191
	ds_read_b128 v[130:133], v142
	ds_read_b128 v[134:137], v142 offset:1024
	ds_read_b128 v[138:141], v142 offset:2048
	ds_read_b128 v[142:145], v142 offset:3072
	ds_read_b128 v[146:149], v158
	ds_read_b128 v[150:153], v158 offset:1024
	ds_read_b128 v[154:157], v158 offset:2048
	ds_read_b128 v[158:161], v158 offset:3072
	s_add_u32 s62, s88, 0x80000
	s_addc_u32 s63, s89, 0
	s_mov_b32 m0, s19
	v_lshl_add_u64 v[236:237], s[62:63], 0, v[174:175]
	ds_read_b128 v[162:165], v224 offset:32768
	ds_read_b128 v[166:169], v224 offset:33792
	ds_read_b128 v[170:173], v224 offset:34816
	ds_read_b128 v[178:181], v224 offset:35840
	ds_read_b128 v[202:205], v224 offset:36864
	ds_read_b128 v[206:209], v224 offset:37888
	ds_read_b128 v[226:229], v224 offset:38912
	ds_read_b128 v[230:233], v224 offset:39936
	global_load_lds_dwordx4 v[236:237], off
	v_lshl_add_u64 v[236:237], s[62:63], 0, v[176:177]
	s_mov_b32 m0, s20
	s_nop 0
	global_load_lds_dwordx4 v[236:237], off
	s_setprio 1
	s_waitcnt vmcnt(8)
	s_waitcnt lgkmcnt(0)
	s_barrier
	v_mfma_f32_16x16x32_bf16 v[126:129], v[130:133], v[162:165], v[126:129]
	v_mfma_f32_16x16x32_bf16 v[56:59], v[138:141], v[162:165], v[56:59]
	v_mfma_f32_16x16x32_bf16 v[122:125], v[130:133], v[170:173], v[122:125]
	v_mfma_f32_16x16x32_bf16 v[52:55], v[138:141], v[170:173], v[52:55]
	v_mfma_f32_16x16x32_bf16 v[118:121], v[130:133], v[202:205], v[118:121]
	v_mfma_f32_16x16x32_bf16 v[60:63], v[138:141], v[202:205], v[60:63]
	v_mfma_f32_16x16x32_bf16 v[114:117], v[130:133], v[226:229], v[114:117]
	v_mfma_f32_16x16x32_bf16 v[44:47], v[138:141], v[226:229], v[44:47]
	v_mfma_f32_16x16x32_bf16 v[126:129], v[134:137], v[166:169], v[126:129]
	v_mfma_f32_16x16x32_bf16 v[56:59], v[142:145], v[166:169], v[56:59]
	v_mfma_f32_16x16x32_bf16 v[122:125], v[134:137], v[178:181], v[122:125]
	v_mfma_f32_16x16x32_bf16 v[52:55], v[142:145], v[178:181], v[52:55]
	v_mfma_f32_16x16x32_bf16 v[118:121], v[134:137], v[206:209], v[118:121]
	v_mfma_f32_16x16x32_bf16 v[60:63], v[142:145], v[206:209], v[60:63]
	v_mfma_f32_16x16x32_bf16 v[114:117], v[134:137], v[230:233], v[114:117]
	v_mfma_f32_16x16x32_bf16 v[44:47], v[142:145], v[230:233], v[44:47]
	v_mfma_f32_16x16x32_bf16 v[110:113], v[146:149], v[162:165], v[110:113]
	v_mfma_f32_16x16x32_bf16 v[40:43], v[154:157], v[162:165], v[40:43]
	v_mfma_f32_16x16x32_bf16 v[106:109], v[146:149], v[170:173], v[106:109]
	v_mfma_f32_16x16x32_bf16 v[36:39], v[154:157], v[170:173], v[36:39]
	v_mfma_f32_16x16x32_bf16 v[102:105], v[146:149], v[202:205], v[102:105]
	v_mfma_f32_16x16x32_bf16 v[48:51], v[154:157], v[202:205], v[48:51]
	v_mfma_f32_16x16x32_bf16 v[98:101], v[146:149], v[226:229], v[98:101]
	v_mfma_f32_16x16x32_bf16 v[32:35], v[154:157], v[226:229], v[32:35]
	v_mfma_f32_16x16x32_bf16 v[110:113], v[150:153], v[166:169], v[110:113]
	v_mfma_f32_16x16x32_bf16 v[40:43], v[158:161], v[166:169], v[40:43]
	v_mfma_f32_16x16x32_bf16 v[106:109], v[150:153], v[178:181], v[106:109]
	v_mfma_f32_16x16x32_bf16 v[36:39], v[158:161], v[178:181], v[36:39]
	v_mfma_f32_16x16x32_bf16 v[102:105], v[150:153], v[206:209], v[102:105]
	v_mfma_f32_16x16x32_bf16 v[48:51], v[158:161], v[206:209], v[48:51]
	v_mfma_f32_16x16x32_bf16 v[98:101], v[150:153], v[230:233], v[98:101]
	v_mfma_f32_16x16x32_bf16 v[32:35], v[158:161], v[230:233], v[32:35]
	s_setprio 0
	s_barrier
	s_add_i32 s62, s67, s5
	v_lshl_add_u64 v[188:189], v[188:189], 0, s[30:31]
	s_mov_b32 m0, s62
	ds_read_b128 v[162:165], v224 offset:49152
	ds_read_b128 v[166:169], v224 offset:50176
	ds_read_b128 v[170:173], v224 offset:51200
	ds_read_b128 v[178:181], v224 offset:52224
	ds_read_b128 v[202:205], v224 offset:53248
	ds_read_b128 v[206:209], v224 offset:54272
	ds_read_b128 v[226:229], v224 offset:55296
	ds_read_b128 v[230:233], v224 offset:56320
	global_load_lds_dwordx4 v[188:189], off
	s_add_i32 m0, s62, 0x2000
	s_add_u32 s62, vcc_lo, 0x80080
	v_lshl_add_u64 v[188:189], v[198:199], 0, s[30:31]
	s_addc_u32 s63, vcc_hi, 0
	s_add_i32 s67, s76, s5
	global_load_lds_dwordx4 v[188:189], off
	v_lshl_add_u64 v[188:189], s[62:63], 0, v[96:97]
	s_mov_b32 m0, s67
	s_nop 0
	global_load_lds_dwordx4 v[188:189], off
	v_lshl_add_u64 v[188:189], s[62:63], 0, v[182:183]
	s_add_i32 m0, s67, 0x2000
	s_nop 0
	global_load_lds_dwordx4 v[188:189], off
	v_lshl_add_u64 v[188:189], v[200:201], 0, s[30:31]
	s_mov_b32 m0, s36
	s_nop 0
	global_load_lds_dwordx4 v[188:189], off
	v_lshl_add_u64 v[188:189], v[234:235], 0, s[30:31]
	s_mov_b32 m0, s37
	s_nop 0
	global_load_lds_dwordx4 v[188:189], off
	s_setprio 1
	s_waitcnt vmcnt(8)
	s_waitcnt lgkmcnt(0)
	s_barrier
	v_mfma_f32_16x16x32_bf16 v[92:95], v[130:133], v[162:165], v[92:95]
	v_mfma_f32_16x16x32_bf16 v[24:27], v[138:141], v[162:165], v[24:27]
	v_mfma_f32_16x16x32_bf16 v[88:91], v[130:133], v[170:173], v[88:91]
	v_mfma_f32_16x16x32_bf16 v[28:31], v[138:141], v[170:173], v[28:31]
	v_mfma_f32_16x16x32_bf16 v[84:87], v[130:133], v[202:205], v[84:87]
	v_mfma_f32_16x16x32_bf16 v[16:19], v[138:141], v[202:205], v[16:19]
	v_mfma_f32_16x16x32_bf16 v[80:83], v[130:133], v[226:229], v[80:83]
	v_mfma_f32_16x16x32_bf16 v[20:23], v[138:141], v[226:229], v[20:23]
	v_mfma_f32_16x16x32_bf16 v[92:95], v[134:137], v[166:169], v[92:95]
	v_mfma_f32_16x16x32_bf16 v[24:27], v[142:145], v[166:169], v[24:27]
	v_mfma_f32_16x16x32_bf16 v[88:91], v[134:137], v[178:181], v[88:91]
	v_mfma_f32_16x16x32_bf16 v[28:31], v[142:145], v[178:181], v[28:31]
	v_mfma_f32_16x16x32_bf16 v[84:87], v[134:137], v[206:209], v[84:87]
	v_mfma_f32_16x16x32_bf16 v[16:19], v[142:145], v[206:209], v[16:19]
	v_mfma_f32_16x16x32_bf16 v[80:83], v[134:137], v[230:233], v[80:83]
	v_mfma_f32_16x16x32_bf16 v[20:23], v[142:145], v[230:233], v[20:23]
	v_mfma_f32_16x16x32_bf16 v[76:79], v[146:149], v[162:165], v[76:79]
	v_mfma_f32_16x16x32_bf16 v[12:15], v[154:157], v[162:165], v[12:15]
	v_mfma_f32_16x16x32_bf16 v[72:75], v[146:149], v[170:173], v[72:75]
	v_mfma_f32_16x16x32_bf16 v[8:11], v[154:157], v[170:173], v[8:11]
	v_mfma_f32_16x16x32_bf16 v[68:71], v[146:149], v[202:205], v[68:71]
	v_mfma_f32_16x16x32_bf16 v[0:3], v[154:157], v[202:205], v[0:3]
	v_mfma_f32_16x16x32_bf16 v[64:67], v[146:149], v[226:229], v[64:67]
	v_mfma_f32_16x16x32_bf16 v[4:7], v[154:157], v[226:229], v[4:7]
	v_mfma_f32_16x16x32_bf16 v[76:79], v[150:153], v[166:169], v[76:79]
	v_mfma_f32_16x16x32_bf16 v[12:15], v[158:161], v[166:169], v[12:15]
	v_mfma_f32_16x16x32_bf16 v[72:75], v[150:153], v[178:181], v[72:75]
	v_mfma_f32_16x16x32_bf16 v[8:11], v[158:161], v[178:181], v[8:11]
	v_mfma_f32_16x16x32_bf16 v[68:71], v[150:153], v[206:209], v[68:71]
	v_mfma_f32_16x16x32_bf16 v[0:3], v[158:161], v[206:209], v[0:3]
	v_mfma_f32_16x16x32_bf16 v[64:67], v[150:153], v[230:233], v[64:67]
	v_mfma_f32_16x16x32_bf16 v[4:7], v[158:161], v[230:233], v[4:7]
	s_setprio 0
	s_barrier
	s_add_i32 s6, s6, 2
	s_add_u32 s2, s2, 0x100
	s_addc_u32 s3, s3, 0
	s_cmp_gt_u32 s6, 29
	s_mov_b64 s[62:63], s[34:35]
	s_cbranch_scc0 .LBB0_1158
	s_nop 0
	s_nop 0
	s_nop 0
	s_nop 0
	s_nop 0
	s_nop 0
	s_nop 0
	s_nop 0
	s_nop 0
	s_nop 0
	s_nop 0
	s_nop 0
	s_and_b64 vcc, exec, s[24:25]
	s_cbranch_vccz .LBB0_1161
	s_barrier

.LBB0_1333:
	s_add_u32 s38, s42, 0x100
	s_addc_u32 s39, s43, 0
	s_add_i32 s13, 0, 0x10000
	s_cmp_eq_u32 s6, 4
	s_cselect_b32 s47, s25, s39
	s_cselect_b32 s46, s24, s38
	s_cselect_b32 s45, s35, s3
	s_cselect_b32 s44, s34, s2
	s_add_i32 s23, 0, 0x14000
	v_add_u32_e32 v152, s13, v136
	v_add_u32_e32 v168, s23, v136
	ds_read_b128 v[140:143], v152
	ds_read_b128 v[144:147], v152 offset:1024
	ds_read_b128 v[148:151], v152 offset:2048
	ds_read_b128 v[152:155], v152 offset:3072
	ds_read_b128 v[156:159], v168
	ds_read_b128 v[160:163], v168 offset:1024
	ds_read_b128 v[164:167], v168 offset:2048
	ds_read_b128 v[168:171], v168 offset:3072
	v_lshl_add_u64 v[198:199], s[42:43], 0, v[132:133]
	s_add_i32 m0, s5, 0xc000
	ds_read_b128 v[172:175], v139
	ds_read_b128 v[176:179], v139 offset:1024
	ds_read_b128 v[180:183], v139 offset:2048
	ds_read_b128 v[184:187], v139 offset:3072
	ds_read_b128 v[188:191], v139 offset:4096
	ds_read_b128 v[192:195], v139 offset:5120
	ds_read_b128 v[202:205], v139 offset:6144
	ds_read_b128 v[206:209], v139 offset:7168
	global_load_lds_dwordx4 v[198:199], off
	v_lshl_add_u64 v[198:199], s[42:43], 0, v[134:135]
	s_add_i32 m0, s5, 0xe000
	s_nop 0
	global_load_lds_dwordx4 v[198:199], off
	s_setprio 1
	s_waitcnt vmcnt(8)
	s_waitcnt lgkmcnt(0)
	s_barrier
	v_mfma_f32_16x16x32_bf16 v[126:129], v[140:143], v[172:175], v[126:129]
	v_mfma_f32_16x16x32_bf16 v[122:125], v[148:151], v[172:175], v[122:125]
	v_mfma_f32_16x16x32_bf16 v[118:121], v[140:143], v[180:183], v[118:121]
	v_mfma_f32_16x16x32_bf16 v[114:117], v[148:151], v[180:183], v[114:117]
	v_mfma_f32_16x16x32_bf16 v[106:109], v[140:143], v[188:191], v[106:109]
	v_mfma_f32_16x16x32_bf16 v[98:101], v[148:151], v[188:191], v[98:101]
	v_mfma_f32_16x16x32_bf16 v[88:91], v[140:143], v[202:205], v[88:91]
	v_mfma_f32_16x16x32_bf16 v[80:83], v[148:151], v[202:205], v[80:83]
	v_mfma_f32_16x16x32_bf16 v[126:129], v[144:147], v[176:179], v[126:129]
	v_mfma_f32_16x16x32_bf16 v[122:125], v[152:155], v[176:179], v[122:125]
	v_mfma_f32_16x16x32_bf16 v[118:121], v[144:147], v[184:187], v[118:121]
	v_mfma_f32_16x16x32_bf16 v[114:117], v[152:155], v[184:187], v[114:117]
	v_mfma_f32_16x16x32_bf16 v[106:109], v[144:147], v[192:195], v[106:109]
	v_mfma_f32_16x16x32_bf16 v[98:101], v[152:155], v[192:195], v[98:101]
	v_mfma_f32_16x16x32_bf16 v[88:91], v[144:147], v[206:209], v[88:91]
	v_mfma_f32_16x16x32_bf16 v[80:83], v[152:155], v[206:209], v[80:83]
	v_mfma_f32_16x16x32_bf16 v[110:113], v[156:159], v[172:175], v[110:113]
	v_mfma_f32_16x16x32_bf16 v[102:105], v[164:167], v[172:175], v[102:105]
	v_mfma_f32_16x16x32_bf16 v[92:95], v[156:159], v[180:183], v[92:95]
	v_mfma_f32_16x16x32_bf16 v[84:87], v[164:167], v[180:183], v[84:87]
	v_mfma_f32_16x16x32_bf16 v[76:79], v[156:159], v[188:191], v[76:79]
	v_mfma_f32_16x16x32_bf16 v[72:75], v[164:167], v[188:191], v[72:75]
	v_mfma_f32_16x16x32_bf16 v[68:71], v[156:159], v[202:205], v[68:71]
	v_mfma_f32_16x16x32_bf16 v[64:67], v[164:167], v[202:205], v[64:67]
	v_mfma_f32_16x16x32_bf16 v[110:113], v[160:163], v[176:179], v[110:113]
	v_mfma_f32_16x16x32_bf16 v[102:105], v[168:171], v[176:179], v[102:105]
	v_mfma_f32_16x16x32_bf16 v[92:95], v[160:163], v[184:187], v[92:95]
	v_mfma_f32_16x16x32_bf16 v[84:87], v[168:171], v[184:187], v[84:87]
	v_mfma_f32_16x16x32_bf16 v[76:79], v[160:163], v[192:195], v[76:79]
	v_mfma_f32_16x16x32_bf16 v[72:75], v[168:171], v[192:195], v[72:75]
	v_mfma_f32_16x16x32_bf16 v[68:71], v[160:163], v[206:209], v[68:71]
	v_mfma_f32_16x16x32_bf16 v[64:67], v[168:171], v[206:209], v[64:67]
	s_setprio 0
	s_barrier
	s_add_i32 s13, s13, s4
	v_lshl_add_u64 v[198:199], s[44:45], 0, v[96:97]
	s_mov_b32 m0, s13
	ds_read_b128 v[172:175], v139 offset:16384
	ds_read_b128 v[176:179], v139 offset:17408
	ds_read_b128 v[180:183], v139 offset:18432
	ds_read_b128 v[184:187], v139 offset:19456
	ds_read_b128 v[188:191], v139 offset:20480
	ds_read_b128 v[192:195], v139 offset:21504
	ds_read_b128 v[202:205], v139 offset:22528
	ds_read_b128 v[206:209], v139 offset:23552
	global_load_lds_dwordx4 v[198:199], off
	s_add_i32 m0, s13, 0x2000
	s_add_u32 s42, s44, 0x160000
	v_lshl_add_u64 v[200:201], s[44:45], 0, v[130:131]
	s_addc_u32 s43, s45, 0
	s_add_i32 s13, s23, s4
	global_load_lds_dwordx4 v[200:201], off
	v_lshl_add_u64 v[214:215], s[42:43], 0, v[96:97]
	s_mov_b32 m0, s13
	v_lshl_add_u64 v[216:217], s[46:47], 0, v[130:131]
	global_load_lds_dwordx4 v[214:215], off
	v_lshl_add_u64 v[214:215], s[42:43], 0, v[130:131]
	s_add_i32 m0, s13, 0x2000
	s_nop 0
	global_load_lds_dwordx4 v[214:215], off
	v_lshl_add_u64 v[214:215], s[46:47], 0, v[96:97]
	s_mov_b32 m0, s5
	s_nop 0
	global_load_lds_dwordx4 v[214:215], off
	s_mov_b32 m0, s17
	s_nop 0
	global_load_lds_dwordx4 v[216:217], off
	s_setprio 1
	s_waitcnt vmcnt(8)
	s_waitcnt lgkmcnt(0)
	s_barrier
	v_mfma_f32_16x16x32_bf16 v[60:63], v[140:143], v[172:175], v[60:63]
	v_mfma_f32_16x16x32_bf16 v[56:59], v[148:151], v[172:175], v[56:59]
	v_mfma_f32_16x16x32_bf16 v[52:55], v[140:143], v[180:183], v[52:55]
	v_mfma_f32_16x16x32_bf16 v[48:51], v[148:151], v[180:183], v[48:51]
	v_mfma_f32_16x16x32_bf16 v[36:39], v[140:143], v[188:191], v[36:39]
	v_mfma_f32_16x16x32_bf16 v[32:35], v[148:151], v[188:191], v[32:35]
	v_mfma_f32_16x16x32_bf16 v[20:23], v[140:143], v[202:205], v[20:23]
	v_mfma_f32_16x16x32_bf16 v[16:19], v[148:151], v[202:205], v[16:19]
	v_mfma_f32_16x16x32_bf16 v[60:63], v[144:147], v[176:179], v[60:63]
	v_mfma_f32_16x16x32_bf16 v[56:59], v[152:155], v[176:179], v[56:59]
	v_mfma_f32_16x16x32_bf16 v[52:55], v[144:147], v[184:187], v[52:55]
	v_mfma_f32_16x16x32_bf16 v[48:51], v[152:155], v[184:187], v[48:51]
	v_mfma_f32_16x16x32_bf16 v[36:39], v[144:147], v[192:195], v[36:39]
	v_mfma_f32_16x16x32_bf16 v[32:35], v[152:155], v[192:195], v[32:35]
	v_mfma_f32_16x16x32_bf16 v[20:23], v[144:147], v[206:209], v[20:23]
	v_mfma_f32_16x16x32_bf16 v[16:19], v[152:155], v[206:209], v[16:19]
	v_mfma_f32_16x16x32_bf16 v[44:47], v[156:159], v[172:175], v[44:47]
	v_mfma_f32_16x16x32_bf16 v[40:43], v[164:167], v[172:175], v[40:43]
	v_mfma_f32_16x16x32_bf16 v[28:31], v[156:159], v[180:183], v[28:31]
	v_mfma_f32_16x16x32_bf16 v[24:27], v[164:167], v[180:183], v[24:27]
	v_mfma_f32_16x16x32_bf16 v[12:15], v[156:159], v[188:191], v[12:15]
	v_mfma_f32_16x16x32_bf16 v[8:11], v[164:167], v[188:191], v[8:11]
	v_mfma_f32_16x16x32_bf16 v[4:7], v[156:159], v[202:205], v[4:7]
	v_mfma_f32_16x16x32_bf16 v[0:3], v[164:167], v[202:205], v[0:3]
	v_mfma_f32_16x16x32_bf16 v[44:47], v[160:163], v[176:179], v[44:47]
	v_mfma_f32_16x16x32_bf16 v[40:43], v[168:171], v[176:179], v[40:43]
	v_mfma_f32_16x16x32_bf16 v[28:31], v[160:163], v[184:187], v[28:31]
	v_mfma_f32_16x16x32_bf16 v[24:27], v[168:171], v[184:187], v[24:27]
	v_mfma_f32_16x16x32_bf16 v[12:15], v[160:163], v[192:195], v[12:15]
	v_mfma_f32_16x16x32_bf16 v[8:11], v[168:171], v[192:195], v[8:11]
	v_mfma_f32_16x16x32_bf16 v[4:7], v[160:163], v[206:209], v[4:7]
	v_mfma_f32_16x16x32_bf16 v[0:3], v[168:171], v[206:209], v[0:3]
	s_setprio 0
	s_barrier
	s_add_i32 s13, 0, 0x18000
	s_add_i32 s23, 0, 0x1c000
	v_add_u32_e32 v152, s13, v136
	v_add_u32_e32 v168, s23, v136
	ds_read_b128 v[140:143], v152
	ds_read_b128 v[144:147], v152 offset:1024
	ds_read_b128 v[148:151], v152 offset:2048
	ds_read_b128 v[152:155], v152 offset:3072
	ds_read_b128 v[156:159], v168
	ds_read_b128 v[160:163], v168 offset:1024
	ds_read_b128 v[164:167], v168 offset:2048
	ds_read_b128 v[168:171], v168 offset:3072
	s_add_u32 s42, s46, 0x160000
	s_addc_u32 s43, s47, 0
	s_mov_b32 m0, s18
	v_lshl_add_u64 v[218:219], s[42:43], 0, v[96:97]
	ds_read_b128 v[172:175], v139 offset:32768
	ds_read_b128 v[176:179], v139 offset:33792
	ds_read_b128 v[180:183], v139 offset:34816
	ds_read_b128 v[184:187], v139 offset:35840
	ds_read_b128 v[188:191], v139 offset:36864
	ds_read_b128 v[192:195], v139 offset:37888
	ds_read_b128 v[202:205], v139 offset:38912
	ds_read_b128 v[206:209], v139 offset:39936
	global_load_lds_dwordx4 v[218:219], off
	v_lshl_add_u64 v[218:219], s[42:43], 0, v[130:131]
	s_mov_b32 m0, s19
	s_nop 0
	global_load_lds_dwordx4 v[218:219], off
	s_setprio 1
	s_waitcnt vmcnt(8)
	s_waitcnt lgkmcnt(0)
	s_barrier
	v_mfma_f32_16x16x32_bf16 v[126:129], v[140:143], v[172:175], v[126:129]
	v_mfma_f32_16x16x32_bf16 v[122:125], v[148:151], v[172:175], v[122:125]
	v_mfma_f32_16x16x32_bf16 v[118:121], v[140:143], v[180:183], v[118:121]
	v_mfma_f32_16x16x32_bf16 v[114:117], v[148:151], v[180:183], v[114:117]
	v_mfma_f32_16x16x32_bf16 v[106:109], v[140:143], v[188:191], v[106:109]
	v_mfma_f32_16x16x32_bf16 v[98:101], v[148:151], v[188:191], v[98:101]
	v_mfma_f32_16x16x32_bf16 v[88:91], v[140:143], v[202:205], v[88:91]
	v_mfma_f32_16x16x32_bf16 v[80:83], v[148:151], v[202:205], v[80:83]
	v_mfma_f32_16x16x32_bf16 v[126:129], v[144:147], v[176:179], v[126:129]
	v_mfma_f32_16x16x32_bf16 v[122:125], v[152:155], v[176:179], v[122:125]
	v_mfma_f32_16x16x32_bf16 v[118:121], v[144:147], v[184:187], v[118:121]
	v_mfma_f32_16x16x32_bf16 v[114:117], v[152:155], v[184:187], v[114:117]
	v_mfma_f32_16x16x32_bf16 v[106:109], v[144:147], v[192:195], v[106:109]
	v_mfma_f32_16x16x32_bf16 v[98:101], v[152:155], v[192:195], v[98:101]
	v_mfma_f32_16x16x32_bf16 v[88:91], v[144:147], v[206:209], v[88:91]
	v_mfma_f32_16x16x32_bf16 v[80:83], v[152:155], v[206:209], v[80:83]
	v_mfma_f32_16x16x32_bf16 v[110:113], v[156:159], v[172:175], v[110:113]
	v_mfma_f32_16x16x32_bf16 v[102:105], v[164:167], v[172:175], v[102:105]
	v_mfma_f32_16x16x32_bf16 v[92:95], v[156:159], v[180:183], v[92:95]
	v_mfma_f32_16x16x32_bf16 v[84:87], v[164:167], v[180:183], v[84:87]
	v_mfma_f32_16x16x32_bf16 v[76:79], v[156:159], v[188:191], v[76:79]
	v_mfma_f32_16x16x32_bf16 v[72:75], v[164:167], v[188:191], v[72:75]
	v_mfma_f32_16x16x32_bf16 v[68:71], v[156:159], v[202:205], v[68:71]
	v_mfma_f32_16x16x32_bf16 v[64:67], v[164:167], v[202:205], v[64:67]
	v_mfma_f32_16x16x32_bf16 v[110:113], v[160:163], v[176:179], v[110:113]
	v_mfma_f32_16x16x32_bf16 v[102:105], v[168:171], v[176:179], v[102:105]
	v_mfma_f32_16x16x32_bf16 v[92:95], v[160:163], v[184:187], v[92:95]
	v_mfma_f32_16x16x32_bf16 v[84:87], v[168:171], v[184:187], v[84:87]
	v_mfma_f32_16x16x32_bf16 v[76:79], v[160:163], v[192:195], v[76:79]
	v_mfma_f32_16x16x32_bf16 v[72:75], v[168:171], v[192:195], v[72:75]
	v_mfma_f32_16x16x32_bf16 v[68:71], v[160:163], v[206:209], v[68:71]
	v_mfma_f32_16x16x32_bf16 v[64:67], v[168:171], v[206:209], v[64:67]
	s_setprio 0
	s_barrier
	s_add_i32 s13, s13, s4
	v_lshl_add_u64 v[198:199], v[198:199], 0, s[30:31]
	s_mov_b32 m0, s13
	ds_read_b128 v[172:175], v139 offset:49152
	ds_read_b128 v[176:179], v139 offset:50176
	ds_read_b128 v[180:183], v139 offset:51200
	ds_read_b128 v[184:187], v139 offset:52224
	ds_read_b128 v[188:191], v139 offset:53248
	ds_read_b128 v[192:195], v139 offset:54272
	ds_read_b128 v[202:205], v139 offset:55296
	ds_read_b128 v[206:209], v139 offset:56320
	global_load_lds_dwordx4 v[198:199], off
	s_add_i32 m0, s13, 0x2000
	s_add_u32 s42, s44, 0x160080
	v_lshl_add_u64 v[198:199], v[200:201], 0, s[30:31]
	s_addc_u32 s43, s45, 0
	s_add_i32 s13, s23, s4
	global_load_lds_dwordx4 v[198:199], off
	v_lshl_add_u64 v[198:199], s[42:43], 0, v[96:97]
	s_mov_b32 m0, s13
	s_nop 0
	global_load_lds_dwordx4 v[198:199], off
	v_lshl_add_u64 v[198:199], s[42:43], 0, v[130:131]
	s_add_i32 m0, s13, 0x2000
	s_nop 0
	global_load_lds_dwordx4 v[198:199], off
	v_lshl_add_u64 v[198:199], v[214:215], 0, s[30:31]
	s_mov_b32 m0, s37
	s_nop 0
	global_load_lds_dwordx4 v[198:199], off
	v_lshl_add_u64 v[198:199], v[216:217], 0, s[30:31]
	s_mov_b32 m0, s40
	s_nop 0
	global_load_lds_dwordx4 v[198:199], off
	s_setprio 1
	s_waitcnt vmcnt(8)
	s_waitcnt lgkmcnt(0)
	s_barrier
	v_mfma_f32_16x16x32_bf16 v[60:63], v[140:143], v[172:175], v[60:63]
	v_mfma_f32_16x16x32_bf16 v[56:59], v[148:151], v[172:175], v[56:59]
	v_mfma_f32_16x16x32_bf16 v[52:55], v[140:143], v[180:183], v[52:55]
	v_mfma_f32_16x16x32_bf16 v[48:51], v[148:151], v[180:183], v[48:51]
	v_mfma_f32_16x16x32_bf16 v[36:39], v[140:143], v[188:191], v[36:39]
	v_mfma_f32_16x16x32_bf16 v[32:35], v[148:151], v[188:191], v[32:35]
	v_mfma_f32_16x16x32_bf16 v[20:23], v[140:143], v[202:205], v[20:23]
	v_mfma_f32_16x16x32_bf16 v[16:19], v[148:151], v[202:205], v[16:19]
	v_mfma_f32_16x16x32_bf16 v[60:63], v[144:147], v[176:179], v[60:63]
	v_mfma_f32_16x16x32_bf16 v[56:59], v[152:155], v[176:179], v[56:59]
	v_mfma_f32_16x16x32_bf16 v[52:55], v[144:147], v[184:187], v[52:55]
	v_mfma_f32_16x16x32_bf16 v[48:51], v[152:155], v[184:187], v[48:51]
	v_mfma_f32_16x16x32_bf16 v[36:39], v[144:147], v[192:195], v[36:39]
	v_mfma_f32_16x16x32_bf16 v[32:35], v[152:155], v[192:195], v[32:35]
	v_mfma_f32_16x16x32_bf16 v[20:23], v[144:147], v[206:209], v[20:23]
	v_mfma_f32_16x16x32_bf16 v[16:19], v[152:155], v[206:209], v[16:19]
	v_mfma_f32_16x16x32_bf16 v[44:47], v[156:159], v[172:175], v[44:47]
	v_mfma_f32_16x16x32_bf16 v[40:43], v[164:167], v[172:175], v[40:43]
	v_mfma_f32_16x16x32_bf16 v[28:31], v[156:159], v[180:183], v[28:31]
	v_mfma_f32_16x16x32_bf16 v[24:27], v[164:167], v[180:183], v[24:27]
	v_mfma_f32_16x16x32_bf16 v[12:15], v[156:159], v[188:191], v[12:15]
	v_mfma_f32_16x16x32_bf16 v[8:11], v[164:167], v[188:191], v[8:11]
	v_mfma_f32_16x16x32_bf16 v[4:7], v[156:159], v[202:205], v[4:7]
	v_mfma_f32_16x16x32_bf16 v[0:3], v[164:167], v[202:205], v[0:3]
	v_mfma_f32_16x16x32_bf16 v[44:47], v[160:163], v[176:179], v[44:47]
	v_mfma_f32_16x16x32_bf16 v[40:43], v[168:171], v[176:179], v[40:43]
	v_mfma_f32_16x16x32_bf16 v[28:31], v[160:163], v[184:187], v[28:31]
	v_mfma_f32_16x16x32_bf16 v[24:27], v[168:171], v[184:187], v[24:27]
	v_mfma_f32_16x16x32_bf16 v[12:15], v[160:163], v[192:195], v[12:15]
	v_mfma_f32_16x16x32_bf16 v[8:11], v[168:171], v[192:195], v[8:11]
	v_mfma_f32_16x16x32_bf16 v[4:7], v[160:163], v[206:209], v[4:7]
	v_mfma_f32_16x16x32_bf16 v[0:3], v[168:171], v[206:209], v[0:3]
	s_setprio 0
	s_barrier
	s_add_i32 s6, s6, 2
	s_add_u32 s2, s2, 0x100
	s_addc_u32 s3, s3, 0
	s_cmp_gt_u32 s6, 5
	s_mov_b64 s[42:43], s[38:39]
	s_cbranch_scc0 .LBB0_1333
	s_nop 0
	s_nop 0
	s_nop 0
	s_nop 0
	s_nop 0
	s_nop 0
	s_nop 0
	s_nop 0
	s_nop 0
	s_nop 0
	s_nop 0
	s_nop 0
	s_and_b64 vcc, exec, s[14:15]
	s_cbranch_vccz .LBB0_1336
	s_barrier

.LBB0_1357:
	s_add_u32 s3, s14, s34
	s_addc_u32 s6, s15, s35
	s_add_u32 s3, s3, 0x100
	s_addc_u32 s6, s6, 0
	s_add_u32 s42, s57, s34
	s_addc_u32 s43, s58, s35
	s_add_i32 s59, 0, 0x10000
	s_cmpk_eq_i32 s34, 0x2b00
	s_cselect_b32 s45, s23, s6
	s_cselect_b32 s44, s22, s3
	v_add_u32_e32 v146, s59, v144
	s_cselect_b32 s43, s25, s43
	s_cselect_b32 s42, s24, s42
	s_add_i32 s3, 0, 0x14000
	ds_read_b128 v[154:157], v146
	ds_read_b128 v[158:161], v146 offset:1024
	ds_read_b128 v[162:165], v146 offset:2048
	ds_read_b128 v[166:169], v146 offset:3072
	v_add_u32_e32 v146, s3, v144
	ds_read_b128 v[174:177], v146
	ds_read_b128 v[178:181], v146 offset:1024
	ds_read_b128 v[182:185], v146 offset:2048
	ds_read_b128 v[186:189], v146 offset:3072
	v_lshl_add_u64 v[146:147], v[140:141], 0, s[34:35]
	s_add_i32 m0, s17, 0xc000
	ds_read_b128 v[190:193], v145
	ds_read_b128 v[202:205], v145 offset:1024
	ds_read_b128 v[206:209], v145 offset:2048
	ds_read_b128 v[214:217], v145 offset:3072
	ds_read_b128 v[218:221], v145 offset:4096
	ds_read_b128 v[222:225], v145 offset:5120
	ds_read_b128 v[226:229], v145 offset:6144
	ds_read_b128 v[230:233], v145 offset:7168
	global_load_lds_dwordx4 v[146:147], off
	v_lshl_add_u64 v[146:147], v[142:143], 0, s[34:35]
	s_add_i32 m0, s17, 0xe000
	s_nop 0
	global_load_lds_dwordx4 v[146:147], off
	s_setprio 1
	s_waitcnt vmcnt(8)
	s_waitcnt lgkmcnt(0)
	s_barrier
	v_mfma_f32_16x16x32_bf16 v[110:113], v[154:157], v[190:193], v[110:113]
	v_mfma_f32_16x16x32_bf16 v[106:109], v[162:165], v[190:193], v[106:109]
	v_mfma_f32_16x16x32_bf16 v[118:121], v[154:157], v[206:209], v[118:121]
	v_mfma_f32_16x16x32_bf16 v[114:117], v[162:165], v[206:209], v[114:117]
	v_mfma_f32_16x16x32_bf16 v[126:129], v[154:157], v[218:221], v[126:129]
	v_mfma_f32_16x16x32_bf16 v[122:125], v[162:165], v[218:221], v[122:125]
	v_mfma_f32_16x16x32_bf16 v[92:95], v[154:157], v[226:229], v[92:95]
	v_mfma_f32_16x16x32_bf16 v[88:91], v[162:165], v[226:229], v[88:91]
	v_mfma_f32_16x16x32_bf16 v[110:113], v[158:161], v[202:205], v[110:113]
	v_mfma_f32_16x16x32_bf16 v[106:109], v[166:169], v[202:205], v[106:109]
	v_mfma_f32_16x16x32_bf16 v[118:121], v[158:161], v[214:217], v[118:121]
	v_mfma_f32_16x16x32_bf16 v[114:117], v[166:169], v[214:217], v[114:117]
	v_mfma_f32_16x16x32_bf16 v[126:129], v[158:161], v[222:225], v[126:129]
	v_mfma_f32_16x16x32_bf16 v[122:125], v[166:169], v[222:225], v[122:125]
	v_mfma_f32_16x16x32_bf16 v[92:95], v[158:161], v[230:233], v[92:95]
	v_mfma_f32_16x16x32_bf16 v[88:91], v[166:169], v[230:233], v[88:91]
	v_mfma_f32_16x16x32_bf16 v[4:7], v[174:177], v[190:193], v[4:7]
	v_mfma_f32_16x16x32_bf16 v[0:3], v[182:185], v[190:193], v[0:3]
	v_mfma_f32_16x16x32_bf16 v[12:15], v[174:177], v[206:209], v[12:15]
	v_mfma_f32_16x16x32_bf16 v[8:11], v[182:185], v[206:209], v[8:11]
	v_mfma_f32_16x16x32_bf16 v[24:27], v[174:177], v[218:221], v[24:27]
	v_mfma_f32_16x16x32_bf16 v[20:23], v[182:185], v[218:221], v[20:23]
	v_mfma_f32_16x16x32_bf16 v[40:43], v[174:177], v[226:229], v[40:43]
	v_mfma_f32_16x16x32_bf16 v[36:39], v[182:185], v[226:229], v[36:39]
	v_mfma_f32_16x16x32_bf16 v[4:7], v[178:181], v[202:205], v[4:7]
	v_mfma_f32_16x16x32_bf16 v[0:3], v[186:189], v[202:205], v[0:3]
	v_mfma_f32_16x16x32_bf16 v[12:15], v[178:181], v[214:217], v[12:15]
	v_mfma_f32_16x16x32_bf16 v[8:11], v[186:189], v[214:217], v[8:11]
	v_mfma_f32_16x16x32_bf16 v[24:27], v[178:181], v[222:225], v[24:27]
	v_mfma_f32_16x16x32_bf16 v[20:23], v[186:189], v[222:225], v[20:23]
	v_mfma_f32_16x16x32_bf16 v[40:43], v[178:181], v[230:233], v[40:43]
	v_mfma_f32_16x16x32_bf16 v[36:39], v[186:189], v[230:233], v[36:39]
	s_setprio 0
	s_barrier
	s_add_i32 s6, s59, s5
	v_lshl_add_u64 v[146:147], s[42:43], 0, v[96:97]
	s_mov_b32 m0, s6
	ds_read_b128 v[190:193], v145 offset:16384
	ds_read_b128 v[202:205], v145 offset:17408
	ds_read_b128 v[206:209], v145 offset:18432
	ds_read_b128 v[214:217], v145 offset:19456
	ds_read_b128 v[218:221], v145 offset:20480
	ds_read_b128 v[222:225], v145 offset:21504
	ds_read_b128 v[226:229], v145 offset:22528
	ds_read_b128 v[230:233], v145 offset:23552
	global_load_lds_dwordx4 v[146:147], off
	s_add_i32 m0, s6, 0x2000
	s_add_u32 s60, s42, 0x160000
	v_lshl_add_u64 v[150:151], s[42:43], 0, v[130:131]
	s_addc_u32 s61, s43, 0
	s_add_i32 s3, s3, s5
	global_load_lds_dwordx4 v[150:151], off
	v_lshl_add_u64 v[170:171], s[60:61], 0, v[96:97]
	s_mov_b32 m0, s3
	v_lshl_add_u64 v[194:195], s[44:45], 0, v[132:133]
	global_load_lds_dwordx4 v[170:171], off
	v_lshl_add_u64 v[170:171], s[60:61], 0, v[130:131]
	s_add_i32 m0, s3, 0x2000
	s_nop 0
	global_load_lds_dwordx4 v[170:171], off
	v_lshl_add_u64 v[170:171], s[44:45], 0, v[134:135]
	s_mov_b32 m0, s17
	s_nop 0
	global_load_lds_dwordx4 v[170:171], off
	s_mov_b32 m0, s18
	s_nop 0
	global_load_lds_dwordx4 v[194:195], off
	s_setprio 1
	s_waitcnt vmcnt(8)
	s_waitcnt lgkmcnt(0)
	s_barrier
	v_mfma_f32_16x16x32_bf16 v[102:105], v[154:157], v[190:193], v[102:105]
	v_mfma_f32_16x16x32_bf16 v[98:101], v[162:165], v[190:193], v[98:101]
	v_mfma_f32_16x16x32_bf16 v[84:87], v[154:157], v[206:209], v[84:87]
	v_mfma_f32_16x16x32_bf16 v[80:83], v[162:165], v[206:209], v[80:83]
	v_mfma_f32_16x16x32_bf16 v[68:71], v[154:157], v[218:221], v[68:71]
	v_mfma_f32_16x16x32_bf16 v[64:67], v[162:165], v[218:221], v[64:67]
	v_mfma_f32_16x16x32_bf16 v[44:47], v[154:157], v[226:229], v[44:47]
	v_mfma_f32_16x16x32_bf16 v[32:35], v[162:165], v[226:229], v[32:35]
	v_mfma_f32_16x16x32_bf16 v[102:105], v[158:161], v[202:205], v[102:105]
	v_mfma_f32_16x16x32_bf16 v[98:101], v[166:169], v[202:205], v[98:101]
	v_mfma_f32_16x16x32_bf16 v[84:87], v[158:161], v[214:217], v[84:87]
	v_mfma_f32_16x16x32_bf16 v[80:83], v[166:169], v[214:217], v[80:83]
	v_mfma_f32_16x16x32_bf16 v[68:71], v[158:161], v[222:225], v[68:71]
	v_mfma_f32_16x16x32_bf16 v[64:67], v[166:169], v[222:225], v[64:67]
	v_mfma_f32_16x16x32_bf16 v[44:47], v[158:161], v[230:233], v[44:47]
	v_mfma_f32_16x16x32_bf16 v[32:35], v[166:169], v[230:233], v[32:35]
	v_mfma_f32_16x16x32_bf16 v[60:63], v[174:177], v[190:193], v[60:63]
	v_mfma_f32_16x16x32_bf16 v[56:59], v[182:185], v[190:193], v[56:59]
	v_mfma_f32_16x16x32_bf16 v[76:79], v[174:177], v[206:209], v[76:79]
	v_mfma_f32_16x16x32_bf16 v[72:75], v[182:185], v[206:209], v[72:75]
	v_mfma_f32_16x16x32_bf16 v[52:55], v[174:177], v[218:221], v[52:55]
	v_mfma_f32_16x16x32_bf16 v[48:51], v[182:185], v[218:221], v[48:51]
	v_mfma_f32_16x16x32_bf16 v[28:31], v[174:177], v[226:229], v[28:31]
	v_mfma_f32_16x16x32_bf16 v[16:19], v[182:185], v[226:229], v[16:19]
	v_mfma_f32_16x16x32_bf16 v[60:63], v[178:181], v[202:205], v[60:63]
	v_mfma_f32_16x16x32_bf16 v[56:59], v[186:189], v[202:205], v[56:59]
	v_mfma_f32_16x16x32_bf16 v[76:79], v[178:181], v[214:217], v[76:79]
	v_mfma_f32_16x16x32_bf16 v[72:75], v[186:189], v[214:217], v[72:75]
	v_mfma_f32_16x16x32_bf16 v[52:55], v[178:181], v[222:225], v[52:55]
	v_mfma_f32_16x16x32_bf16 v[48:51], v[186:189], v[222:225], v[48:51]
	v_mfma_f32_16x16x32_bf16 v[28:31], v[178:181], v[230:233], v[28:31]
	v_mfma_f32_16x16x32_bf16 v[16:19], v[186:189], v[230:233], v[16:19]
	s_setprio 0
	s_barrier
	s_add_i32 s3, 0, 0x18000
	v_add_u32_e32 v149, s3, v144
	s_add_i32 s6, 0, 0x1c000
	ds_read_b128 v[154:157], v149
	ds_read_b128 v[158:161], v149 offset:1024
	ds_read_b128 v[162:165], v149 offset:2048
	ds_read_b128 v[166:169], v149 offset:3072
	v_add_u32_e32 v149, s6, v144
	ds_read_b128 v[174:177], v149
	ds_read_b128 v[178:181], v149 offset:1024
	ds_read_b128 v[182:185], v149 offset:2048
	ds_read_b128 v[186:189], v149 offset:3072
	s_add_u32 s44, s44, 0x160000
	s_addc_u32 s45, s45, 0
	s_mov_b32 m0, s19
	v_lshl_add_u64 v[198:199], s[44:45], 0, v[134:135]
	ds_read_b128 v[190:193], v145 offset:32768
	ds_read_b128 v[202:205], v145 offset:33792
	ds_read_b128 v[206:209], v145 offset:34816
	ds_read_b128 v[214:217], v145 offset:35840
	ds_read_b128 v[218:221], v145 offset:36864
	ds_read_b128 v[222:225], v145 offset:37888
	ds_read_b128 v[226:229], v145 offset:38912
	ds_read_b128 v[230:233], v145 offset:39936
	global_load_lds_dwordx4 v[198:199], off
	v_lshl_add_u64 v[198:199], s[44:45], 0, v[132:133]
	s_mov_b32 m0, s20
	s_nop 0
	global_load_lds_dwordx4 v[198:199], off
	s_setprio 1
	s_waitcnt vmcnt(8)
	s_waitcnt lgkmcnt(0)
	s_barrier
	v_mfma_f32_16x16x32_bf16 v[110:113], v[154:157], v[190:193], v[110:113]
	v_mfma_f32_16x16x32_bf16 v[106:109], v[162:165], v[190:193], v[106:109]
	v_mfma_f32_16x16x32_bf16 v[118:121], v[154:157], v[206:209], v[118:121]
	v_mfma_f32_16x16x32_bf16 v[114:117], v[162:165], v[206:209], v[114:117]
	v_mfma_f32_16x16x32_bf16 v[126:129], v[154:157], v[218:221], v[126:129]
	v_mfma_f32_16x16x32_bf16 v[122:125], v[162:165], v[218:221], v[122:125]
	v_mfma_f32_16x16x32_bf16 v[92:95], v[154:157], v[226:229], v[92:95]
	v_mfma_f32_16x16x32_bf16 v[88:91], v[162:165], v[226:229], v[88:91]
	v_mfma_f32_16x16x32_bf16 v[110:113], v[158:161], v[202:205], v[110:113]
	v_mfma_f32_16x16x32_bf16 v[106:109], v[166:169], v[202:205], v[106:109]
	v_mfma_f32_16x16x32_bf16 v[118:121], v[158:161], v[214:217], v[118:121]
	v_mfma_f32_16x16x32_bf16 v[114:117], v[166:169], v[214:217], v[114:117]
	v_mfma_f32_16x16x32_bf16 v[126:129], v[158:161], v[222:225], v[126:129]
	v_mfma_f32_16x16x32_bf16 v[122:125], v[166:169], v[222:225], v[122:125]
	v_mfma_f32_16x16x32_bf16 v[92:95], v[158:161], v[230:233], v[92:95]
	v_mfma_f32_16x16x32_bf16 v[88:91], v[166:169], v[230:233], v[88:91]
	v_mfma_f32_16x16x32_bf16 v[4:7], v[174:177], v[190:193], v[4:7]
	v_mfma_f32_16x16x32_bf16 v[0:3], v[182:185], v[190:193], v[0:3]
	v_mfma_f32_16x16x32_bf16 v[12:15], v[174:177], v[206:209], v[12:15]
	v_mfma_f32_16x16x32_bf16 v[8:11], v[182:185], v[206:209], v[8:11]
	v_mfma_f32_16x16x32_bf16 v[24:27], v[174:177], v[218:221], v[24:27]
	v_mfma_f32_16x16x32_bf16 v[20:23], v[182:185], v[218:221], v[20:23]
	v_mfma_f32_16x16x32_bf16 v[40:43], v[174:177], v[226:229], v[40:43]
	v_mfma_f32_16x16x32_bf16 v[36:39], v[182:185], v[226:229], v[36:39]
	v_mfma_f32_16x16x32_bf16 v[4:7], v[178:181], v[202:205], v[4:7]
	v_mfma_f32_16x16x32_bf16 v[0:3], v[186:189], v[202:205], v[0:3]
	v_mfma_f32_16x16x32_bf16 v[12:15], v[178:181], v[214:217], v[12:15]
	v_mfma_f32_16x16x32_bf16 v[8:11], v[186:189], v[214:217], v[8:11]
	v_mfma_f32_16x16x32_bf16 v[24:27], v[178:181], v[222:225], v[24:27]
	v_mfma_f32_16x16x32_bf16 v[20:23], v[186:189], v[222:225], v[20:23]
	v_mfma_f32_16x16x32_bf16 v[40:43], v[178:181], v[230:233], v[40:43]
	v_mfma_f32_16x16x32_bf16 v[36:39], v[186:189], v[230:233], v[36:39]
	s_setprio 0
	s_barrier
	s_add_i32 s3, s3, s5
	v_lshl_add_u64 v[146:147], v[146:147], 0, s[30:31]
	s_mov_b32 m0, s3
	ds_read_b128 v[190:193], v145 offset:49152
	ds_read_b128 v[202:205], v145 offset:50176
	ds_read_b128 v[206:209], v145 offset:51200
	ds_read_b128 v[214:217], v145 offset:52224
	ds_read_b128 v[218:221], v145 offset:53248
	ds_read_b128 v[222:225], v145 offset:54272
	ds_read_b128 v[226:229], v145 offset:55296
	ds_read_b128 v[230:233], v145 offset:56320
	global_load_lds_dwordx4 v[146:147], off
	s_add_i32 m0, s3, 0x2000
	s_add_u32 s42, s42, 0x160080
	v_lshl_add_u64 v[146:147], v[150:151], 0, s[30:31]
	s_addc_u32 s43, s43, 0
	s_add_i32 s3, s6, s5
	global_load_lds_dwordx4 v[146:147], off
	v_lshl_add_u64 v[146:147], s[42:43], 0, v[96:97]
	s_mov_b32 m0, s3
	s_nop 0
	global_load_lds_dwordx4 v[146:147], off
	v_lshl_add_u64 v[146:147], s[42:43], 0, v[130:131]
	s_add_i32 m0, s3, 0x2000
	s_nop 0
	global_load_lds_dwordx4 v[146:147], off
	v_lshl_add_u64 v[146:147], v[170:171], 0, s[30:31]
	s_mov_b32 m0, s37
	s_nop 0
	global_load_lds_dwordx4 v[146:147], off
	v_lshl_add_u64 v[146:147], v[194:195], 0, s[30:31]
	s_mov_b32 m0, s52
	s_nop 0
	global_load_lds_dwordx4 v[146:147], off
	s_setprio 1
	s_waitcnt vmcnt(8)
	s_waitcnt lgkmcnt(0)
	s_barrier
	v_mfma_f32_16x16x32_bf16 v[102:105], v[154:157], v[190:193], v[102:105]
	v_mfma_f32_16x16x32_bf16 v[98:101], v[162:165], v[190:193], v[98:101]
	v_mfma_f32_16x16x32_bf16 v[84:87], v[154:157], v[206:209], v[84:87]
	v_mfma_f32_16x16x32_bf16 v[80:83], v[162:165], v[206:209], v[80:83]
	v_mfma_f32_16x16x32_bf16 v[68:71], v[154:157], v[218:221], v[68:71]
	v_mfma_f32_16x16x32_bf16 v[64:67], v[162:165], v[218:221], v[64:67]
	v_mfma_f32_16x16x32_bf16 v[44:47], v[154:157], v[226:229], v[44:47]
	v_mfma_f32_16x16x32_bf16 v[32:35], v[162:165], v[226:229], v[32:35]
	v_mfma_f32_16x16x32_bf16 v[102:105], v[158:161], v[202:205], v[102:105]
	v_mfma_f32_16x16x32_bf16 v[98:101], v[166:169], v[202:205], v[98:101]
	v_mfma_f32_16x16x32_bf16 v[84:87], v[158:161], v[214:217], v[84:87]
	v_mfma_f32_16x16x32_bf16 v[80:83], v[166:169], v[214:217], v[80:83]
	v_mfma_f32_16x16x32_bf16 v[68:71], v[158:161], v[222:225], v[68:71]
	v_mfma_f32_16x16x32_bf16 v[64:67], v[166:169], v[222:225], v[64:67]
	v_mfma_f32_16x16x32_bf16 v[44:47], v[158:161], v[230:233], v[44:47]
	v_mfma_f32_16x16x32_bf16 v[32:35], v[166:169], v[230:233], v[32:35]
	v_mfma_f32_16x16x32_bf16 v[60:63], v[174:177], v[190:193], v[60:63]
	v_mfma_f32_16x16x32_bf16 v[56:59], v[182:185], v[190:193], v[56:59]
	v_mfma_f32_16x16x32_bf16 v[76:79], v[174:177], v[206:209], v[76:79]
	v_mfma_f32_16x16x32_bf16 v[72:75], v[182:185], v[206:209], v[72:75]
	v_mfma_f32_16x16x32_bf16 v[52:55], v[174:177], v[218:221], v[52:55]
	v_mfma_f32_16x16x32_bf16 v[48:51], v[182:185], v[218:221], v[48:51]
	v_mfma_f32_16x16x32_bf16 v[28:31], v[174:177], v[226:229], v[28:31]
	v_mfma_f32_16x16x32_bf16 v[16:19], v[182:185], v[226:229], v[16:19]
	v_mfma_f32_16x16x32_bf16 v[60:63], v[178:181], v[202:205], v[60:63]
	v_mfma_f32_16x16x32_bf16 v[56:59], v[186:189], v[202:205], v[56:59]
	v_mfma_f32_16x16x32_bf16 v[76:79], v[178:181], v[214:217], v[76:79]
	v_mfma_f32_16x16x32_bf16 v[72:75], v[186:189], v[214:217], v[72:75]
	v_mfma_f32_16x16x32_bf16 v[52:55], v[178:181], v[222:225], v[52:55]
	v_mfma_f32_16x16x32_bf16 v[48:51], v[186:189], v[222:225], v[48:51]
	v_mfma_f32_16x16x32_bf16 v[28:31], v[178:181], v[230:233], v[28:31]
	v_mfma_f32_16x16x32_bf16 v[16:19], v[186:189], v[230:233], v[16:19]
	s_setprio 0
	s_barrier
	s_add_i32 s2, s2, 2
	s_add_u32 s34, s34, 0x100
	s_addc_u32 s35, s35, 0
	s_cmpk_gt_u32 s2, 0x55
	s_cbranch_scc0 .LBB0_1357
	s_nop 0
	s_nop 0
	s_nop 0
	s_nop 0
	s_nop 0
	s_nop 0
	s_nop 0
	s_nop 0
	s_nop 0
	s_nop 0
	s_nop 0
	s_nop 0
	s_and_b64 vcc, exec, s[12:13]
	s_cbranch_vccz .LBB0_1360
	s_barrier

.LBB0_1413:
	s_add_u32 s24, s22, 0x100
	s_addc_u32 s25, s23, 0
	s_add_i32 s45, 0, 0x10000
	s_cmpk_eq_i32 s6, 0x54
	s_cselect_b32 s39, s13, s25
	s_cselect_b32 s38, s12, s24
	s_cselect_b32 s35, s15, s3
	s_cselect_b32 s34, s14, s2
	s_add_i32 s46, 0, 0x14000
	v_add_u32_e32 v142, s45, v155
	v_add_u32_e32 v152, s46, v155
	ds_read_b128 v[130:133], v142
	ds_read_b128 v[134:137], v142 offset:1024
	ds_read_b128 v[138:141], v142 offset:2048
	ds_read_b128 v[142:145], v142 offset:3072
	ds_read_b128 v[158:161], v152
	ds_read_b128 v[162:165], v152 offset:1024
	ds_read_b128 v[166:169], v152 offset:2048
	ds_read_b128 v[170:173], v152 offset:3072
	v_lshl_add_u64 v[152:153], s[22:23], 0, v[148:149]
	s_add_i32 m0, s5, 0xc000
	ds_read_b128 v[174:177], v157
	ds_read_b128 v[178:181], v157 offset:1024
	ds_read_b128 v[182:185], v157 offset:2048
	ds_read_b128 v[186:189], v157 offset:3072
	ds_read_b128 v[190:193], v157 offset:4096
	ds_read_b128 v[202:205], v157 offset:5120
	ds_read_b128 v[206:209], v157 offset:6144
	ds_read_b128 v[214:217], v157 offset:7168
	global_load_lds_dwordx4 v[152:153], off
	v_lshl_add_u64 v[152:153], s[22:23], 0, v[150:151]
	s_add_i32 m0, s5, 0xe000
	s_nop 0
	global_load_lds_dwordx4 v[152:153], off
	s_setprio 1
	s_waitcnt vmcnt(8)
	s_waitcnt lgkmcnt(0)
	s_barrier
	v_mfma_f32_16x16x32_bf16 v[126:129], v[130:133], v[174:177], v[126:129]
	v_mfma_f32_16x16x32_bf16 v[122:125], v[138:141], v[174:177], v[122:125]
	v_mfma_f32_16x16x32_bf16 v[114:117], v[130:133], v[182:185], v[114:117]
	v_mfma_f32_16x16x32_bf16 v[110:113], v[138:141], v[182:185], v[110:113]
	v_mfma_f32_16x16x32_bf16 v[98:101], v[130:133], v[190:193], v[98:101]
	v_mfma_f32_16x16x32_bf16 v[92:95], v[138:141], v[190:193], v[92:95]
	v_mfma_f32_16x16x32_bf16 v[80:83], v[130:133], v[206:209], v[80:83]
	v_mfma_f32_16x16x32_bf16 v[76:79], v[138:141], v[206:209], v[76:79]
	v_mfma_f32_16x16x32_bf16 v[126:129], v[134:137], v[178:181], v[126:129]
	v_mfma_f32_16x16x32_bf16 v[122:125], v[142:145], v[178:181], v[122:125]
	v_mfma_f32_16x16x32_bf16 v[114:117], v[134:137], v[186:189], v[114:117]
	v_mfma_f32_16x16x32_bf16 v[110:113], v[142:145], v[186:189], v[110:113]
	v_mfma_f32_16x16x32_bf16 v[98:101], v[134:137], v[202:205], v[98:101]
	v_mfma_f32_16x16x32_bf16 v[92:95], v[142:145], v[202:205], v[92:95]
	v_mfma_f32_16x16x32_bf16 v[80:83], v[134:137], v[214:217], v[80:83]
	v_mfma_f32_16x16x32_bf16 v[76:79], v[142:145], v[214:217], v[76:79]
	v_mfma_f32_16x16x32_bf16 v[118:121], v[158:161], v[174:177], v[118:121]
	v_mfma_f32_16x16x32_bf16 v[106:109], v[166:169], v[174:177], v[106:109]
	v_mfma_f32_16x16x32_bf16 v[102:105], v[158:161], v[182:185], v[102:105]
	v_mfma_f32_16x16x32_bf16 v[88:91], v[166:169], v[182:185], v[88:91]
	v_mfma_f32_16x16x32_bf16 v[84:87], v[158:161], v[190:193], v[84:87]
	v_mfma_f32_16x16x32_bf16 v[72:75], v[166:169], v[190:193], v[72:75]
	v_mfma_f32_16x16x32_bf16 v[68:71], v[158:161], v[206:209], v[68:71]
	v_mfma_f32_16x16x32_bf16 v[64:67], v[166:169], v[206:209], v[64:67]
	v_mfma_f32_16x16x32_bf16 v[118:121], v[162:165], v[178:181], v[118:121]
	v_mfma_f32_16x16x32_bf16 v[106:109], v[170:173], v[178:181], v[106:109]
	v_mfma_f32_16x16x32_bf16 v[102:105], v[162:165], v[186:189], v[102:105]
	v_mfma_f32_16x16x32_bf16 v[88:91], v[170:173], v[186:189], v[88:91]
	v_mfma_f32_16x16x32_bf16 v[84:87], v[162:165], v[202:205], v[84:87]
	v_mfma_f32_16x16x32_bf16 v[72:75], v[170:173], v[202:205], v[72:75]
	v_mfma_f32_16x16x32_bf16 v[68:71], v[162:165], v[214:217], v[68:71]
	v_mfma_f32_16x16x32_bf16 v[64:67], v[170:173], v[214:217], v[64:67]
	s_setprio 0
	s_barrier
	s_add_i32 s22, s45, s4
	v_lshl_add_u64 v[152:153], s[34:35], 0, v[96:97]
	s_mov_b32 m0, s22
	ds_read_b128 v[174:177], v157 offset:16384
	ds_read_b128 v[178:181], v157 offset:17408
	ds_read_b128 v[182:185], v157 offset:18432
	ds_read_b128 v[186:189], v157 offset:19456
	ds_read_b128 v[190:193], v157 offset:20480
	ds_read_b128 v[202:205], v157 offset:21504
	ds_read_b128 v[206:209], v157 offset:22528
	ds_read_b128 v[214:217], v157 offset:23552
	global_load_lds_dwordx4 v[152:153], off
	s_add_i32 m0, s22, 0x2000
	s_add_u32 s22, s34, 0x160000
	v_lshl_add_u64 v[194:195], s[34:35], 0, v[146:147]
	s_addc_u32 s23, s35, 0
	s_add_i32 s45, s46, s4
	global_load_lds_dwordx4 v[194:195], off
	v_lshl_add_u64 v[198:199], s[22:23], 0, v[96:97]
	s_mov_b32 m0, s45
	v_lshl_add_u64 v[200:201], s[38:39], 0, v[146:147]
	global_load_lds_dwordx4 v[198:199], off
	v_lshl_add_u64 v[198:199], s[22:23], 0, v[146:147]
	s_add_i32 m0, s45, 0x2000
	s_nop 0
	global_load_lds_dwordx4 v[198:199], off
	v_lshl_add_u64 v[198:199], s[38:39], 0, v[96:97]
	s_mov_b32 m0, s5
	s_nop 0
	global_load_lds_dwordx4 v[198:199], off
	s_mov_b32 m0, s17
	s_nop 0
	global_load_lds_dwordx4 v[200:201], off
	s_setprio 1
	s_waitcnt vmcnt(8)
	s_waitcnt lgkmcnt(0)
	s_barrier
	v_mfma_f32_16x16x32_bf16 v[60:63], v[130:133], v[174:177], v[60:63]
	v_mfma_f32_16x16x32_bf16 v[56:59], v[138:141], v[174:177], v[56:59]
	v_mfma_f32_16x16x32_bf16 v[48:51], v[130:133], v[182:185], v[48:51]
	v_mfma_f32_16x16x32_bf16 v[44:47], v[138:141], v[182:185], v[44:47]
	v_mfma_f32_16x16x32_bf16 v[32:35], v[130:133], v[190:193], v[32:35]
	v_mfma_f32_16x16x32_bf16 v[28:31], v[138:141], v[190:193], v[28:31]
	v_mfma_f32_16x16x32_bf16 v[16:19], v[130:133], v[206:209], v[16:19]
	v_mfma_f32_16x16x32_bf16 v[12:15], v[138:141], v[206:209], v[12:15]
	v_mfma_f32_16x16x32_bf16 v[60:63], v[134:137], v[178:181], v[60:63]
	v_mfma_f32_16x16x32_bf16 v[56:59], v[142:145], v[178:181], v[56:59]
	v_mfma_f32_16x16x32_bf16 v[48:51], v[134:137], v[186:189], v[48:51]
	v_mfma_f32_16x16x32_bf16 v[44:47], v[142:145], v[186:189], v[44:47]
	v_mfma_f32_16x16x32_bf16 v[32:35], v[134:137], v[202:205], v[32:35]
	v_mfma_f32_16x16x32_bf16 v[28:31], v[142:145], v[202:205], v[28:31]
	v_mfma_f32_16x16x32_bf16 v[16:19], v[134:137], v[214:217], v[16:19]
	v_mfma_f32_16x16x32_bf16 v[12:15], v[142:145], v[214:217], v[12:15]
	v_mfma_f32_16x16x32_bf16 v[52:55], v[158:161], v[174:177], v[52:55]
	v_mfma_f32_16x16x32_bf16 v[40:43], v[166:169], v[174:177], v[40:43]
	v_mfma_f32_16x16x32_bf16 v[36:39], v[158:161], v[182:185], v[36:39]
	v_mfma_f32_16x16x32_bf16 v[24:27], v[166:169], v[182:185], v[24:27]
	v_mfma_f32_16x16x32_bf16 v[20:23], v[158:161], v[190:193], v[20:23]
	v_mfma_f32_16x16x32_bf16 v[8:11], v[166:169], v[190:193], v[8:11]
	v_mfma_f32_16x16x32_bf16 v[4:7], v[158:161], v[206:209], v[4:7]
	v_mfma_f32_16x16x32_bf16 v[0:3], v[166:169], v[206:209], v[0:3]
	v_mfma_f32_16x16x32_bf16 v[52:55], v[162:165], v[178:181], v[52:55]
	v_mfma_f32_16x16x32_bf16 v[40:43], v[170:173], v[178:181], v[40:43]
	v_mfma_f32_16x16x32_bf16 v[36:39], v[162:165], v[186:189], v[36:39]
	v_mfma_f32_16x16x32_bf16 v[24:27], v[170:173], v[186:189], v[24:27]
	v_mfma_f32_16x16x32_bf16 v[20:23], v[162:165], v[202:205], v[20:23]
	v_mfma_f32_16x16x32_bf16 v[8:11], v[170:173], v[202:205], v[8:11]
	v_mfma_f32_16x16x32_bf16 v[4:7], v[162:165], v[214:217], v[4:7]
	v_mfma_f32_16x16x32_bf16 v[0:3], v[170:173], v[214:217], v[0:3]
	s_setprio 0
	s_barrier
	s_add_i32 s45, 0, 0x18000
	s_add_i32 s46, 0, 0x1c000
	v_add_u32_e32 v142, s45, v155
	v_add_u32_e32 v170, s46, v155
	ds_read_b128 v[130:133], v142
	ds_read_b128 v[134:137], v142 offset:1024
	ds_read_b128 v[138:141], v142 offset:2048
	ds_read_b128 v[142:145], v142 offset:3072
	ds_read_b128 v[158:161], v170
	ds_read_b128 v[162:165], v170 offset:1024
	ds_read_b128 v[166:169], v170 offset:2048
	ds_read_b128 v[170:173], v170 offset:3072
	s_add_u32 s22, s38, 0x160000
	s_addc_u32 s23, s39, 0
	s_mov_b32 m0, s18
	v_lshl_add_u64 v[218:219], s[22:23], 0, v[96:97]
	ds_read_b128 v[174:177], v157 offset:32768
	ds_read_b128 v[178:181], v157 offset:33792
	ds_read_b128 v[182:185], v157 offset:34816
	ds_read_b128 v[186:189], v157 offset:35840
	ds_read_b128 v[190:193], v157 offset:36864
	ds_read_b128 v[202:205], v157 offset:37888
	ds_read_b128 v[206:209], v157 offset:38912
	ds_read_b128 v[214:217], v157 offset:39936
	global_load_lds_dwordx4 v[218:219], off
	v_lshl_add_u64 v[218:219], s[22:23], 0, v[146:147]
	s_mov_b32 m0, s19
	s_nop 0
	global_load_lds_dwordx4 v[218:219], off
	s_setprio 1
	s_waitcnt vmcnt(8)
	s_waitcnt lgkmcnt(0)
	s_barrier
	v_mfma_f32_16x16x32_bf16 v[126:129], v[130:133], v[174:177], v[126:129]
	v_mfma_f32_16x16x32_bf16 v[122:125], v[138:141], v[174:177], v[122:125]
	v_mfma_f32_16x16x32_bf16 v[114:117], v[130:133], v[182:185], v[114:117]
	v_mfma_f32_16x16x32_bf16 v[110:113], v[138:141], v[182:185], v[110:113]
	v_mfma_f32_16x16x32_bf16 v[98:101], v[130:133], v[190:193], v[98:101]
	v_mfma_f32_16x16x32_bf16 v[92:95], v[138:141], v[190:193], v[92:95]
	v_mfma_f32_16x16x32_bf16 v[80:83], v[130:133], v[206:209], v[80:83]
	v_mfma_f32_16x16x32_bf16 v[76:79], v[138:141], v[206:209], v[76:79]
	v_mfma_f32_16x16x32_bf16 v[126:129], v[134:137], v[178:181], v[126:129]
	v_mfma_f32_16x16x32_bf16 v[122:125], v[142:145], v[178:181], v[122:125]
	v_mfma_f32_16x16x32_bf16 v[114:117], v[134:137], v[186:189], v[114:117]
	v_mfma_f32_16x16x32_bf16 v[110:113], v[142:145], v[186:189], v[110:113]
	v_mfma_f32_16x16x32_bf16 v[98:101], v[134:137], v[202:205], v[98:101]
	v_mfma_f32_16x16x32_bf16 v[92:95], v[142:145], v[202:205], v[92:95]
	v_mfma_f32_16x16x32_bf16 v[80:83], v[134:137], v[214:217], v[80:83]
	v_mfma_f32_16x16x32_bf16 v[76:79], v[142:145], v[214:217], v[76:79]
	v_mfma_f32_16x16x32_bf16 v[118:121], v[158:161], v[174:177], v[118:121]
	v_mfma_f32_16x16x32_bf16 v[106:109], v[166:169], v[174:177], v[106:109]
	v_mfma_f32_16x16x32_bf16 v[102:105], v[158:161], v[182:185], v[102:105]
	v_mfma_f32_16x16x32_bf16 v[88:91], v[166:169], v[182:185], v[88:91]
	v_mfma_f32_16x16x32_bf16 v[84:87], v[158:161], v[190:193], v[84:87]
	v_mfma_f32_16x16x32_bf16 v[72:75], v[166:169], v[190:193], v[72:75]
	v_mfma_f32_16x16x32_bf16 v[68:71], v[158:161], v[206:209], v[68:71]
	v_mfma_f32_16x16x32_bf16 v[64:67], v[166:169], v[206:209], v[64:67]
	v_mfma_f32_16x16x32_bf16 v[118:121], v[162:165], v[178:181], v[118:121]
	v_mfma_f32_16x16x32_bf16 v[106:109], v[170:173], v[178:181], v[106:109]
	v_mfma_f32_16x16x32_bf16 v[102:105], v[162:165], v[186:189], v[102:105]
	v_mfma_f32_16x16x32_bf16 v[88:91], v[170:173], v[186:189], v[88:91]
	v_mfma_f32_16x16x32_bf16 v[84:87], v[162:165], v[202:205], v[84:87]
	v_mfma_f32_16x16x32_bf16 v[72:75], v[170:173], v[202:205], v[72:75]
	v_mfma_f32_16x16x32_bf16 v[68:71], v[162:165], v[214:217], v[68:71]
	v_mfma_f32_16x16x32_bf16 v[64:67], v[170:173], v[214:217], v[64:67]
	s_setprio 0
	s_barrier
	s_add_i32 s22, s45, s4
	v_lshl_add_u64 v[152:153], v[152:153], 0, s[30:31]
	s_mov_b32 m0, s22
	ds_read_b128 v[174:177], v157 offset:49152
	ds_read_b128 v[178:181], v157 offset:50176
	ds_read_b128 v[182:185], v157 offset:51200
	ds_read_b128 v[186:189], v157 offset:52224
	ds_read_b128 v[190:193], v157 offset:53248
	ds_read_b128 v[202:205], v157 offset:54272
	ds_read_b128 v[206:209], v157 offset:55296
	ds_read_b128 v[214:217], v157 offset:56320
	global_load_lds_dwordx4 v[152:153], off
	s_add_i32 m0, s22, 0x2000
	s_add_u32 s22, s34, 0x160080
	v_lshl_add_u64 v[152:153], v[194:195], 0, s[30:31]
	s_addc_u32 s23, s35, 0
	s_add_i32 s34, s46, s4
	global_load_lds_dwordx4 v[152:153], off
	v_lshl_add_u64 v[152:153], s[22:23], 0, v[96:97]
	s_mov_b32 m0, s34
	s_nop 0
	global_load_lds_dwordx4 v[152:153], off
	v_lshl_add_u64 v[152:153], s[22:23], 0, v[146:147]
	s_add_i32 m0, s34, 0x2000
	s_nop 0
	global_load_lds_dwordx4 v[152:153], off
	v_lshl_add_u64 v[152:153], v[198:199], 0, s[30:31]
	s_mov_b32 m0, s20
	s_nop 0
	global_load_lds_dwordx4 v[152:153], off
	v_lshl_add_u64 v[152:153], v[200:201], 0, s[30:31]
	s_mov_b32 m0, s36
	s_nop 0
	global_load_lds_dwordx4 v[152:153], off
	s_setprio 1
	s_waitcnt vmcnt(8)
	s_waitcnt lgkmcnt(0)
	s_barrier
	v_mfma_f32_16x16x32_bf16 v[60:63], v[130:133], v[174:177], v[60:63]
	v_mfma_f32_16x16x32_bf16 v[56:59], v[138:141], v[174:177], v[56:59]
	v_mfma_f32_16x16x32_bf16 v[48:51], v[130:133], v[182:185], v[48:51]
	v_mfma_f32_16x16x32_bf16 v[44:47], v[138:141], v[182:185], v[44:47]
	v_mfma_f32_16x16x32_bf16 v[32:35], v[130:133], v[190:193], v[32:35]
	v_mfma_f32_16x16x32_bf16 v[28:31], v[138:141], v[190:193], v[28:31]
	v_mfma_f32_16x16x32_bf16 v[16:19], v[130:133], v[206:209], v[16:19]
	v_mfma_f32_16x16x32_bf16 v[12:15], v[138:141], v[206:209], v[12:15]
	v_mfma_f32_16x16x32_bf16 v[60:63], v[134:137], v[178:181], v[60:63]
	v_mfma_f32_16x16x32_bf16 v[56:59], v[142:145], v[178:181], v[56:59]
	v_mfma_f32_16x16x32_bf16 v[48:51], v[134:137], v[186:189], v[48:51]
	v_mfma_f32_16x16x32_bf16 v[44:47], v[142:145], v[186:189], v[44:47]
	v_mfma_f32_16x16x32_bf16 v[32:35], v[134:137], v[202:205], v[32:35]
	v_mfma_f32_16x16x32_bf16 v[28:31], v[142:145], v[202:205], v[28:31]
	v_mfma_f32_16x16x32_bf16 v[16:19], v[134:137], v[214:217], v[16:19]
	v_mfma_f32_16x16x32_bf16 v[12:15], v[142:145], v[214:217], v[12:15]
	v_mfma_f32_16x16x32_bf16 v[52:55], v[158:161], v[174:177], v[52:55]
	v_mfma_f32_16x16x32_bf16 v[40:43], v[166:169], v[174:177], v[40:43]
	v_mfma_f32_16x16x32_bf16 v[36:39], v[158:161], v[182:185], v[36:39]
	v_mfma_f32_16x16x32_bf16 v[24:27], v[166:169], v[182:185], v[24:27]
	v_mfma_f32_16x16x32_bf16 v[20:23], v[158:161], v[190:193], v[20:23]
	v_mfma_f32_16x16x32_bf16 v[8:11], v[166:169], v[190:193], v[8:11]
	v_mfma_f32_16x16x32_bf16 v[4:7], v[158:161], v[206:209], v[4:7]
	v_mfma_f32_16x16x32_bf16 v[0:3], v[166:169], v[206:209], v[0:3]
	v_mfma_f32_16x16x32_bf16 v[52:55], v[162:165], v[178:181], v[52:55]
	v_mfma_f32_16x16x32_bf16 v[40:43], v[170:173], v[178:181], v[40:43]
	v_mfma_f32_16x16x32_bf16 v[36:39], v[162:165], v[186:189], v[36:39]
	v_mfma_f32_16x16x32_bf16 v[24:27], v[170:173], v[186:189], v[24:27]
	v_mfma_f32_16x16x32_bf16 v[20:23], v[162:165], v[202:205], v[20:23]
	v_mfma_f32_16x16x32_bf16 v[8:11], v[170:173], v[202:205], v[8:11]
	v_mfma_f32_16x16x32_bf16 v[4:7], v[162:165], v[214:217], v[4:7]
	v_mfma_f32_16x16x32_bf16 v[0:3], v[170:173], v[214:217], v[0:3]
	s_setprio 0
	s_barrier
	s_add_i32 s6, s6, 2
	s_add_u32 s2, s2, 0x100
	s_addc_u32 s3, s3, 0
	s_cmpk_gt_u32 s6, 0x55
	s_mov_b64 s[22:23], s[24:25]
	s_cbranch_scc0 .LBB0_1413
	s_nop 0
	s_nop 0
	s_nop 0
	s_nop 0
	s_nop 0
	s_nop 0
	s_nop 0
	s_nop 0
	s_nop 0
	s_nop 0
	s_nop 0
	s_nop 0
	s_and_b64 vcc, exec, s[10:11]
	s_cbranch_vccz .LBB0_1416
	s_barrier
